# v27 + redundant s[100:101] recomputations removed (14 SALU pairs) + the four LDS read-base adds of the P2 K-loop hoisted
# baseline (speedup 1.0000x reference)
.LBB0_424:
	s_ashr_i32 s37, s36, 31
	s_lshl_b64 s[0:1], s[36:37], 21
	s_add_u32 s38, s25, s0
	s_addc_u32 s39, s26, s1
	s_and_b64 s[0:1], s[2:3], exec
	s_cselect_b32 s49, s39, s47
	s_cselect_b32 s48, s38, s46
	s_ashr_i32 s35, s34, 31
	s_lshl_b64 s[0:1], s[34:35], 21
	s_add_u32 s40, s27, s0
	s_addc_u32 s41, s58, s1
	s_and_b64 s[0:1], s[2:3], exec
	v_mov_b32_e32 v0, 0
	s_cselect_b32 s51, s41, s45
	s_cselect_b32 s50, s40, s44
	s_mov_b32 s13, -2
	s_mov_b32 s35, 0
	v_mov_b64_e32 v[0:1], 0
	v_mov_b64_e32 v[2:3], 0
	v_mov_b64_e32 v[4:5], 0
	v_mov_b64_e32 v[6:7], 0
	v_mov_b64_e32 v[8:9], 0
	v_mov_b64_e32 v[10:11], 0
	v_mov_b64_e32 v[12:13], 0
	v_mov_b64_e32 v[14:15], 0
	v_mov_b64_e32 v[16:17], 0
	v_mov_b64_e32 v[18:19], 0
	v_mov_b64_e32 v[20:21], 0
	v_mov_b64_e32 v[22:23], 0
	v_mov_b64_e32 v[24:25], 0
	v_mov_b64_e32 v[26:27], 0
	v_mov_b64_e32 v[28:29], 0
	v_mov_b64_e32 v[30:31], 0
	v_mov_b64_e32 v[32:33], 0
	v_mov_b64_e32 v[34:35], 0
	v_mov_b64_e32 v[36:37], 0
	v_mov_b64_e32 v[38:39], 0
	v_mov_b64_e32 v[40:41], 0
	v_mov_b64_e32 v[42:43], 0
	v_mov_b64_e32 v[44:45], 0
	v_mov_b64_e32 v[46:47], 0
	v_mov_b64_e32 v[48:49], 0
	v_mov_b64_e32 v[50:51], 0
	v_mov_b64_e32 v[52:53], 0
	v_mov_b64_e32 v[54:55], 0
	v_mov_b64_e32 v[56:57], 0
	v_mov_b64_e32 v[58:59], 0
	v_mov_b64_e32 v[60:61], 0
	v_mov_b64_e32 v[62:63], 0
	v_mov_b64_e32 v[64:65], 0
	v_mov_b64_e32 v[66:67], 0
	v_mov_b64_e32 v[68:69], 0
	v_mov_b64_e32 v[70:71], 0
	v_mov_b64_e32 v[72:73], 0
	v_mov_b64_e32 v[74:75], 0
	v_mov_b64_e32 v[76:77], 0
	v_mov_b64_e32 v[78:79], 0
	v_mov_b64_e32 v[80:81], 0
	v_mov_b64_e32 v[82:83], 0
	v_mov_b64_e32 v[84:85], 0
	v_mov_b64_e32 v[86:87], 0
	v_mov_b64_e32 v[88:89], 0
	v_mov_b64_e32 v[90:91], 0
	v_mov_b64_e32 v[92:93], 0
	v_mov_b64_e32 v[94:95], 0
	v_mov_b64_e32 v[96:97], 0
	v_mov_b64_e32 v[98:99], 0
	v_mov_b64_e32 v[100:101], 0
	v_mov_b64_e32 v[102:103], 0
	v_mov_b64_e32 v[104:105], 0
	v_mov_b64_e32 v[106:107], 0
	v_mov_b64_e32 v[108:109], 0
	v_mov_b64_e32 v[110:111], 0
	v_mov_b64_e32 v[112:113], 0
	v_mov_b64_e32 v[114:115], 0
	v_mov_b64_e32 v[116:117], 0
	v_mov_b64_e32 v[118:119], 0
	v_mov_b64_e32 v[120:121], 0
	v_mov_b64_e32 v[122:123], 0
	v_mov_b64_e32 v[124:125], 0
	v_mov_b64_e32 v[126:127], 0
	v_add_u32_e32 v214, 0x10000, v143
	v_add_u32_e32 v215, 0x14000, v143
	v_add_u32_e32 v216, 0x18000, v143
	v_add_u32_e32 v217, 0x1c000, v143
	s_branch .LBB0_426
.LBB0_425:
	ds_read_b128 v[146:149], v214
	ds_read_b128 v[150:153], v214 offset:1024
	ds_read_b128 v[154:157], v214 offset:2048
	ds_read_b128 v[158:161], v214 offset:3072
	ds_read_b128 v[162:165], v215
	ds_read_b128 v[166:169], v215 offset:1024
	ds_read_b128 v[170:173], v215 offset:2048
	ds_read_b128 v[174:177], v215 offset:3072
	s_add_i32 s13, s13, 2
	s_lshr_b32 s0, s13, 6
	s_mul_hi_u32 s1, s0, 0x8200000
	s_mul_i32 s0, s0, 0x8200000
	s_add_u32 s0, s46, s0
	s_addc_u32 s1, s47, s1
	s_and_b32 s35, s35, 0x1f00
	s_add_u32 s0, s0, s35
	s_addc_u32 s1, s1, 0
	s_add_u32 s0, s0, 0x100080
	s_addc_u32 s1, s1, 0
	s_add_i32 m0, s43, 0xc000
	ds_read_b128 v[178:181], v145
	ds_read_b128 v[182:185], v145 offset:1024
	ds_read_b128 v[186:189], v145 offset:2048
	ds_read_b128 v[190:193], v145 offset:3072
	ds_read_b128 v[194:197], v145 offset:4096
	ds_read_b128 v[198:201], v145 offset:5120
	ds_read_b128 v[202:205], v145 offset:6144
	global_load_lds_dwordx4 v128, s[0:1]
	s_add_i32 m0, s43, 0xe000
	ds_read_b128 v[206:209], v145 offset:7168
	global_load_lds_dwordx4 v132, s[0:1]
	s_waitcnt vmcnt(8)
	s_waitcnt lgkmcnt(0)
	s_setprio 3
	s_barrier
	v_mfma_f32_16x16x32_bf16 v[124:127], v[146:149], v[178:181], v[124:127]
	v_mfma_f32_16x16x32_bf16 v[120:123], v[154:157], v[178:181], v[120:123]
	v_mfma_f32_16x16x32_bf16 v[116:119], v[146:149], v[186:189], v[116:119]
	v_mfma_f32_16x16x32_bf16 v[108:111], v[154:157], v[186:189], v[108:111]
	v_mfma_f32_16x16x32_bf16 v[100:103], v[146:149], v[194:197], v[100:103]
	v_mfma_f32_16x16x32_bf16 v[92:95], v[154:157], v[194:197], v[92:95]
	v_mfma_f32_16x16x32_bf16 v[84:87], v[146:149], v[202:205], v[84:87]
	v_mfma_f32_16x16x32_bf16 v[76:79], v[154:157], v[202:205], v[76:79]
	v_mfma_f32_16x16x32_bf16 v[124:127], v[150:153], v[182:185], v[124:127]
	v_mfma_f32_16x16x32_bf16 v[120:123], v[158:161], v[182:185], v[120:123]
	v_mfma_f32_16x16x32_bf16 v[116:119], v[150:153], v[190:193], v[116:119]
	v_mfma_f32_16x16x32_bf16 v[108:111], v[158:161], v[190:193], v[108:111]
	v_mfma_f32_16x16x32_bf16 v[100:103], v[150:153], v[198:201], v[100:103]
	v_mfma_f32_16x16x32_bf16 v[92:95], v[158:161], v[198:201], v[92:95]
	v_mfma_f32_16x16x32_bf16 v[84:87], v[150:153], v[206:209], v[84:87]
	v_mfma_f32_16x16x32_bf16 v[76:79], v[158:161], v[206:209], v[76:79]
	s_setprio 0
	s_setprio 3
	v_mfma_f32_16x16x32_bf16 v[112:115], v[162:165], v[178:181], v[112:115]
	v_mfma_f32_16x16x32_bf16 v[104:107], v[170:173], v[178:181], v[104:107]
	v_mfma_f32_16x16x32_bf16 v[96:99], v[162:165], v[186:189], v[96:99]
	v_mfma_f32_16x16x32_bf16 v[88:91], v[170:173], v[186:189], v[88:91]
	v_mfma_f32_16x16x32_bf16 v[80:83], v[162:165], v[194:197], v[80:83]
	v_mfma_f32_16x16x32_bf16 v[72:75], v[170:173], v[194:197], v[72:75]
	v_mfma_f32_16x16x32_bf16 v[68:71], v[162:165], v[202:205], v[68:71]
	v_mfma_f32_16x16x32_bf16 v[64:67], v[170:173], v[202:205], v[64:67]
	v_mfma_f32_16x16x32_bf16 v[112:115], v[166:169], v[182:185], v[112:115]
	v_mfma_f32_16x16x32_bf16 v[104:107], v[174:177], v[182:185], v[104:107]
	v_mfma_f32_16x16x32_bf16 v[96:99], v[166:169], v[190:193], v[96:99]
	v_mfma_f32_16x16x32_bf16 v[88:91], v[174:177], v[190:193], v[88:91]
	v_mfma_f32_16x16x32_bf16 v[80:83], v[166:169], v[198:201], v[80:83]
	v_mfma_f32_16x16x32_bf16 v[72:75], v[174:177], v[198:201], v[72:75]
	v_mfma_f32_16x16x32_bf16 v[68:71], v[166:169], v[206:209], v[68:71]
	v_mfma_f32_16x16x32_bf16 v[64:67], v[174:177], v[206:209], v[64:67]
	s_barrier
	s_setprio 0
	s_add_i32 s0, s67, s59
	s_mov_b32 m0, s0
	ds_read_b128 v[178:181], v145 offset:16384
	ds_read_b128 v[182:185], v145 offset:17408
	ds_read_b128 v[186:189], v145 offset:18432
	ds_read_b128 v[190:193], v145 offset:19456
	ds_read_b128 v[194:197], v145 offset:20480
	global_load_lds_dwordx4 v130, s[52:53]
	s_add_i32 m0, s0, 0x2000
	s_add_u32 s0, s52, 0x100000
	s_addc_u32 s1, s53, 0
	s_add_i32 s35, s68, s59
	global_load_lds_dwordx4 v134, s[52:53]
	s_mov_b32 m0, s35
	s_nop 0
	global_load_lds_dwordx4 v130, s[0:1]
	s_add_i32 m0, s35, 0x2000
	ds_read_b128 v[206:209], v145 offset:23552
	global_load_lds_dwordx4 v134, s[0:1]
	s_mov_b32 m0, s43
	ds_read_b128 v[202:205], v145 offset:22528
	global_load_lds_dwordx4 v128, s[54:55]
	s_mov_b32 m0, s62
	ds_read_b128 v[198:201], v145 offset:21504
	global_load_lds_dwordx4 v132, s[54:55]
	s_waitcnt vmcnt(8)
	s_waitcnt lgkmcnt(0)
	s_setprio 3
	s_barrier
	v_mfma_f32_16x16x32_bf16 v[60:63], v[146:149], v[178:181], v[60:63]
	v_mfma_f32_16x16x32_bf16 v[56:59], v[154:157], v[178:181], v[56:59]
	v_mfma_f32_16x16x32_bf16 v[52:55], v[146:149], v[186:189], v[52:55]
	v_mfma_f32_16x16x32_bf16 v[44:47], v[154:157], v[186:189], v[44:47]
	v_mfma_f32_16x16x32_bf16 v[36:39], v[146:149], v[194:197], v[36:39]
	v_mfma_f32_16x16x32_bf16 v[28:31], v[154:157], v[194:197], v[28:31]
	v_mfma_f32_16x16x32_bf16 v[20:23], v[146:149], v[202:205], v[20:23]
	v_mfma_f32_16x16x32_bf16 v[12:15], v[154:157], v[202:205], v[12:15]
	v_mfma_f32_16x16x32_bf16 v[60:63], v[150:153], v[182:185], v[60:63]
	v_mfma_f32_16x16x32_bf16 v[56:59], v[158:161], v[182:185], v[56:59]
	v_mfma_f32_16x16x32_bf16 v[52:55], v[150:153], v[190:193], v[52:55]
	v_mfma_f32_16x16x32_bf16 v[44:47], v[158:161], v[190:193], v[44:47]
	v_mfma_f32_16x16x32_bf16 v[36:39], v[150:153], v[198:201], v[36:39]
	v_mfma_f32_16x16x32_bf16 v[28:31], v[158:161], v[198:201], v[28:31]
	v_mfma_f32_16x16x32_bf16 v[20:23], v[150:153], v[206:209], v[20:23]
	v_mfma_f32_16x16x32_bf16 v[12:15], v[158:161], v[206:209], v[12:15]
	s_setprio 0
	s_setprio 3
	v_mfma_f32_16x16x32_bf16 v[48:51], v[162:165], v[178:181], v[48:51]
	v_mfma_f32_16x16x32_bf16 v[40:43], v[170:173], v[178:181], v[40:43]
	v_mfma_f32_16x16x32_bf16 v[32:35], v[162:165], v[186:189], v[32:35]
	v_mfma_f32_16x16x32_bf16 v[24:27], v[170:173], v[186:189], v[24:27]
	v_mfma_f32_16x16x32_bf16 v[16:19], v[162:165], v[194:197], v[16:19]
	v_mfma_f32_16x16x32_bf16 v[8:11], v[170:173], v[194:197], v[8:11]
	v_mfma_f32_16x16x32_bf16 v[4:7], v[162:165], v[202:205], v[4:7]
	v_mfma_f32_16x16x32_bf16 v[0:3], v[170:173], v[202:205], v[0:3]
	v_mfma_f32_16x16x32_bf16 v[48:51], v[166:169], v[182:185], v[48:51]
	v_mfma_f32_16x16x32_bf16 v[40:43], v[174:177], v[182:185], v[40:43]
	v_mfma_f32_16x16x32_bf16 v[32:35], v[166:169], v[190:193], v[32:35]
	v_mfma_f32_16x16x32_bf16 v[24:27], v[174:177], v[190:193], v[24:27]
	v_mfma_f32_16x16x32_bf16 v[16:19], v[166:169], v[198:201], v[16:19]
	v_mfma_f32_16x16x32_bf16 v[8:11], v[174:177], v[198:201], v[8:11]
	v_mfma_f32_16x16x32_bf16 v[4:7], v[166:169], v[206:209], v[4:7]
	v_mfma_f32_16x16x32_bf16 v[0:3], v[174:177], v[206:209], v[0:3]
	s_barrier
	s_setprio 0
	s_add_i32 s35, 0, 0x18000
	s_add_i32 s37, 0, 0x1c000
	ds_read_b128 v[146:149], v216
	ds_read_b128 v[150:153], v216 offset:1024
	ds_read_b128 v[154:157], v216 offset:2048
	ds_read_b128 v[158:161], v216 offset:3072
	ds_read_b128 v[162:165], v217
	ds_read_b128 v[166:169], v217 offset:1024
	ds_read_b128 v[170:173], v217 offset:2048
	ds_read_b128 v[174:177], v217 offset:3072
	s_add_u32 s0, s54, 0x100000
	s_addc_u32 s1, s55, 0
	s_mov_b32 m0, s63
	ds_read_b128 v[178:181], v145 offset:32768
	ds_read_b128 v[182:185], v145 offset:33792
	ds_read_b128 v[186:189], v145 offset:34816
	ds_read_b128 v[190:193], v145 offset:35840
	ds_read_b128 v[194:197], v145 offset:36864
	ds_read_b128 v[198:201], v145 offset:37888
	ds_read_b128 v[202:205], v145 offset:38912
	global_load_lds_dwordx4 v128, s[0:1]
	s_mov_b32 m0, s64
	ds_read_b128 v[206:209], v145 offset:39936
	global_load_lds_dwordx4 v132, s[0:1]
	s_waitcnt vmcnt(8)
	s_waitcnt lgkmcnt(0)
	s_setprio 3
	s_barrier
	v_mfma_f32_16x16x32_bf16 v[124:127], v[146:149], v[178:181], v[124:127]
	v_mfma_f32_16x16x32_bf16 v[120:123], v[154:157], v[178:181], v[120:123]
	v_mfma_f32_16x16x32_bf16 v[116:119], v[146:149], v[186:189], v[116:119]
	v_mfma_f32_16x16x32_bf16 v[108:111], v[154:157], v[186:189], v[108:111]
	v_mfma_f32_16x16x32_bf16 v[100:103], v[146:149], v[194:197], v[100:103]
	v_mfma_f32_16x16x32_bf16 v[92:95], v[154:157], v[194:197], v[92:95]
	v_mfma_f32_16x16x32_bf16 v[84:87], v[146:149], v[202:205], v[84:87]
	v_mfma_f32_16x16x32_bf16 v[76:79], v[154:157], v[202:205], v[76:79]
	v_mfma_f32_16x16x32_bf16 v[124:127], v[150:153], v[182:185], v[124:127]
	v_mfma_f32_16x16x32_bf16 v[120:123], v[158:161], v[182:185], v[120:123]
	v_mfma_f32_16x16x32_bf16 v[116:119], v[150:153], v[190:193], v[116:119]
	v_mfma_f32_16x16x32_bf16 v[108:111], v[158:161], v[190:193], v[108:111]
	v_mfma_f32_16x16x32_bf16 v[100:103], v[150:153], v[198:201], v[100:103]
	v_mfma_f32_16x16x32_bf16 v[92:95], v[158:161], v[198:201], v[92:95]
	v_mfma_f32_16x16x32_bf16 v[84:87], v[150:153], v[206:209], v[84:87]
	v_mfma_f32_16x16x32_bf16 v[76:79], v[158:161], v[206:209], v[76:79]
	s_setprio 0
	s_setprio 3
	v_mfma_f32_16x16x32_bf16 v[112:115], v[162:165], v[178:181], v[112:115]
	v_mfma_f32_16x16x32_bf16 v[104:107], v[170:173], v[178:181], v[104:107]
	v_mfma_f32_16x16x32_bf16 v[96:99], v[162:165], v[186:189], v[96:99]
	v_mfma_f32_16x16x32_bf16 v[88:91], v[170:173], v[186:189], v[88:91]
	v_mfma_f32_16x16x32_bf16 v[80:83], v[162:165], v[194:197], v[80:83]
	v_mfma_f32_16x16x32_bf16 v[72:75], v[170:173], v[194:197], v[72:75]
	v_mfma_f32_16x16x32_bf16 v[68:71], v[162:165], v[202:205], v[68:71]
	v_mfma_f32_16x16x32_bf16 v[64:67], v[170:173], v[202:205], v[64:67]
	v_mfma_f32_16x16x32_bf16 v[112:115], v[166:169], v[182:185], v[112:115]
	v_mfma_f32_16x16x32_bf16 v[104:107], v[174:177], v[182:185], v[104:107]
	v_mfma_f32_16x16x32_bf16 v[96:99], v[166:169], v[190:193], v[96:99]
	v_mfma_f32_16x16x32_bf16 v[88:91], v[174:177], v[190:193], v[88:91]
	v_mfma_f32_16x16x32_bf16 v[80:83], v[166:169], v[198:201], v[80:83]
	v_mfma_f32_16x16x32_bf16 v[72:75], v[174:177], v[198:201], v[72:75]
	v_mfma_f32_16x16x32_bf16 v[68:71], v[166:169], v[206:209], v[68:71]
	v_mfma_f32_16x16x32_bf16 v[64:67], v[174:177], v[206:209], v[64:67]
	s_barrier
	s_setprio 0
	s_add_i32 s0, s35, s59
	s_add_u32 s100, s52, 0x80
	s_addc_u32 s101, s53, 0
	s_mov_b32 m0, s0
	ds_read_b128 v[178:181], v145 offset:49152
	ds_read_b128 v[182:185], v145 offset:50176
	ds_read_b128 v[186:189], v145 offset:51200
	ds_read_b128 v[190:193], v145 offset:52224
	global_load_lds_dwordx4 v130, s[100:101]
	s_add_i32 m0, s0, 0x2000
	s_add_u32 s0, s52, 0x100080
	s_addc_u32 s1, s53, 0
	s_add_i32 s35, s37, s59
	global_load_lds_dwordx4 v134, s[100:101]
	s_mov_b32 m0, s35
	ds_read_b128 v[206:209], v145 offset:56320
	global_load_lds_dwordx4 v130, s[0:1]
	s_add_i32 m0, s35, 0x2000
	ds_read_b128 v[202:205], v145 offset:55296
	global_load_lds_dwordx4 v134, s[0:1]
	s_add_u32 s100, s54, 0x80
	s_addc_u32 s101, s55, 0
	s_mov_b32 m0, s60
	ds_read_b128 v[198:201], v145 offset:54272
	global_load_lds_dwordx4 v128, s[100:101]
	s_mov_b32 m0, s65
	ds_read_b128 v[194:197], v145 offset:53248
	global_load_lds_dwordx4 v132, s[100:101]
	s_waitcnt vmcnt(8)
	s_waitcnt lgkmcnt(0)
	s_setprio 3
	s_barrier
	v_mfma_f32_16x16x32_bf16 v[60:63], v[146:149], v[178:181], v[60:63]
	v_mfma_f32_16x16x32_bf16 v[56:59], v[154:157], v[178:181], v[56:59]
	v_mfma_f32_16x16x32_bf16 v[52:55], v[146:149], v[186:189], v[52:55]
	v_mfma_f32_16x16x32_bf16 v[44:47], v[154:157], v[186:189], v[44:47]
	v_mfma_f32_16x16x32_bf16 v[36:39], v[146:149], v[194:197], v[36:39]
	v_mfma_f32_16x16x32_bf16 v[28:31], v[154:157], v[194:197], v[28:31]
	v_mfma_f32_16x16x32_bf16 v[20:23], v[146:149], v[202:205], v[20:23]
	v_mfma_f32_16x16x32_bf16 v[12:15], v[154:157], v[202:205], v[12:15]
	v_mfma_f32_16x16x32_bf16 v[60:63], v[150:153], v[182:185], v[60:63]
	v_mfma_f32_16x16x32_bf16 v[56:59], v[158:161], v[182:185], v[56:59]
	v_mfma_f32_16x16x32_bf16 v[52:55], v[150:153], v[190:193], v[52:55]
	v_mfma_f32_16x16x32_bf16 v[44:47], v[158:161], v[190:193], v[44:47]
	v_mfma_f32_16x16x32_bf16 v[36:39], v[150:153], v[198:201], v[36:39]
	v_mfma_f32_16x16x32_bf16 v[28:31], v[158:161], v[198:201], v[28:31]
	v_mfma_f32_16x16x32_bf16 v[20:23], v[150:153], v[206:209], v[20:23]
	v_mfma_f32_16x16x32_bf16 v[12:15], v[158:161], v[206:209], v[12:15]
	s_setprio 0
	s_setprio 3
	v_mfma_f32_16x16x32_bf16 v[48:51], v[162:165], v[178:181], v[48:51]
	v_mfma_f32_16x16x32_bf16 v[40:43], v[170:173], v[178:181], v[40:43]
	v_mfma_f32_16x16x32_bf16 v[32:35], v[162:165], v[186:189], v[32:35]
	v_mfma_f32_16x16x32_bf16 v[24:27], v[170:173], v[186:189], v[24:27]
	v_mfma_f32_16x16x32_bf16 v[16:19], v[162:165], v[194:197], v[16:19]
	v_mfma_f32_16x16x32_bf16 v[8:11], v[170:173], v[194:197], v[8:11]
	v_mfma_f32_16x16x32_bf16 v[4:7], v[162:165], v[202:205], v[4:7]
	v_mfma_f32_16x16x32_bf16 v[0:3], v[170:173], v[202:205], v[0:3]
	v_mfma_f32_16x16x32_bf16 v[48:51], v[166:169], v[182:185], v[48:51]
	v_mfma_f32_16x16x32_bf16 v[40:43], v[174:177], v[182:185], v[40:43]
	v_mfma_f32_16x16x32_bf16 v[32:35], v[166:169], v[190:193], v[32:35]
	v_mfma_f32_16x16x32_bf16 v[24:27], v[174:177], v[190:193], v[24:27]
	v_mfma_f32_16x16x32_bf16 v[16:19], v[166:169], v[198:201], v[16:19]
	v_mfma_f32_16x16x32_bf16 v[8:11], v[174:177], v[198:201], v[8:11]
	v_mfma_f32_16x16x32_bf16 v[4:7], v[166:169], v[206:209], v[4:7]
	v_mfma_f32_16x16x32_bf16 v[0:3], v[174:177], v[206:209], v[0:3]
	s_barrier
	s_setprio 0
	s_cmpk_gt_u32 s13, 0xa9
	s_mov_b32 s35, s4
	s_cbranch_scc1 .LBB0_432

.LBB0_677:
	ds_read_b128 v[156:159], v152
	ds_read_b128 v[160:163], v152 offset:1024
	ds_read_b128 v[164:167], v152 offset:2048
	ds_read_b128 v[168:171], v152 offset:3072
	ds_read_b128 v[172:175], v153
	ds_read_b128 v[176:179], v153 offset:1024
	ds_read_b128 v[180:183], v153 offset:2048
	ds_read_b128 v[184:187], v153 offset:3072
	s_add_u32 s0, s36, 0xfff00080
	s_addc_u32 s1, s37, -1
	s_cmp_eq_u32 s61, 60
	s_cselect_b32 s41, s56, s1
	s_cselect_b32 s40, s57, s0
	s_cselect_b32 s39, s15, s60
	s_cselect_b32 s38, s58, s59
	s_add_i32 m0, s31, 0xc000
	ds_read_b128 v[188:191], v154
	ds_read_b128 v[192:195], v154 offset:1024
	ds_read_b128 v[196:199], v154 offset:2048
	ds_read_b128 v[200:203], v154 offset:3072
	ds_read_b128 v[204:207], v154 offset:4096
	ds_read_b128 v[208:211], v154 offset:5120
	ds_read_b128 v[212:215], v154 offset:6144
	global_load_lds_dwordx4 v138, s[36:37]
	s_add_i32 m0, s31, 0xe000
	ds_read_b128 v[216:219], v154 offset:7168
	global_load_lds_dwordx4 v140, s[36:37]
	s_waitcnt vmcnt(8)
	s_waitcnt lgkmcnt(0)
	s_setprio 3
	s_barrier
	v_mfma_f32_16x16x32_bf16 v[124:127], v[156:159], v[188:191], v[124:127]
	v_mfma_f32_16x16x32_bf16 v[120:123], v[164:167], v[188:191], v[120:123]
	v_mfma_f32_16x16x32_bf16 v[108:111], v[156:159], v[196:199], v[108:111]
	v_mfma_f32_16x16x32_bf16 v[104:107], v[164:167], v[196:199], v[104:107]
	v_mfma_f32_16x16x32_bf16 v[92:95], v[156:159], v[204:207], v[92:95]
	v_mfma_f32_16x16x32_bf16 v[88:91], v[164:167], v[204:207], v[88:91]
	v_mfma_f32_16x16x32_bf16 v[76:79], v[156:159], v[212:215], v[76:79]
	v_mfma_f32_16x16x32_bf16 v[72:75], v[164:167], v[212:215], v[72:75]
	v_mfma_f32_16x16x32_bf16 v[124:127], v[160:163], v[192:195], v[124:127]
	v_mfma_f32_16x16x32_bf16 v[120:123], v[168:171], v[192:195], v[120:123]
	v_mfma_f32_16x16x32_bf16 v[108:111], v[160:163], v[200:203], v[108:111]
	v_mfma_f32_16x16x32_bf16 v[104:107], v[168:171], v[200:203], v[104:107]
	v_mfma_f32_16x16x32_bf16 v[92:95], v[160:163], v[208:211], v[92:95]
	v_mfma_f32_16x16x32_bf16 v[88:91], v[168:171], v[208:211], v[88:91]
	v_mfma_f32_16x16x32_bf16 v[76:79], v[160:163], v[216:219], v[76:79]
	v_mfma_f32_16x16x32_bf16 v[72:75], v[168:171], v[216:219], v[72:75]
	s_setprio 0
	s_setprio 3
	v_mfma_f32_16x16x32_bf16 v[116:119], v[172:175], v[188:191], v[116:119]
	v_mfma_f32_16x16x32_bf16 v[112:115], v[180:183], v[188:191], v[112:115]
	v_mfma_f32_16x16x32_bf16 v[100:103], v[172:175], v[196:199], v[100:103]
	v_mfma_f32_16x16x32_bf16 v[96:99], v[180:183], v[196:199], v[96:99]
	v_mfma_f32_16x16x32_bf16 v[84:87], v[172:175], v[204:207], v[84:87]
	v_mfma_f32_16x16x32_bf16 v[80:83], v[180:183], v[204:207], v[80:83]
	v_mfma_f32_16x16x32_bf16 v[68:71], v[172:175], v[212:215], v[68:71]
	v_mfma_f32_16x16x32_bf16 v[64:67], v[180:183], v[212:215], v[64:67]
	v_mfma_f32_16x16x32_bf16 v[116:119], v[176:179], v[192:195], v[116:119]
	v_mfma_f32_16x16x32_bf16 v[112:115], v[184:187], v[192:195], v[112:115]
	v_mfma_f32_16x16x32_bf16 v[100:103], v[176:179], v[200:203], v[100:103]
	v_mfma_f32_16x16x32_bf16 v[96:99], v[184:187], v[200:203], v[96:99]
	v_mfma_f32_16x16x32_bf16 v[84:87], v[176:179], v[208:211], v[84:87]
	v_mfma_f32_16x16x32_bf16 v[80:83], v[184:187], v[208:211], v[80:83]
	v_mfma_f32_16x16x32_bf16 v[68:71], v[176:179], v[216:219], v[68:71]
	v_mfma_f32_16x16x32_bf16 v[64:67], v[184:187], v[216:219], v[64:67]
	s_barrier
	s_setprio 0
	s_add_i32 s0, s51, s43
	s_mov_b32 m0, s0
	ds_read_b128 v[188:191], v154 offset:16384
	ds_read_b128 v[192:195], v154 offset:17408
	ds_read_b128 v[196:199], v154 offset:18432
	ds_read_b128 v[200:203], v154 offset:19456
	ds_read_b128 v[204:207], v154 offset:20480
	global_load_lds_dwordx4 v130, s[38:39]
	s_add_i32 m0, s0, 0x2000
	s_add_u32 s0, s38, 0x100000
	s_addc_u32 s1, s39, 0
	s_add_i32 s62, s52, s43
	global_load_lds_dwordx4 v134, s[38:39]
	s_mov_b32 m0, s62
	s_nop 0
	global_load_lds_dwordx4 v130, s[0:1]
	s_add_i32 m0, s62, 0x2000
	ds_read_b128 v[216:219], v154 offset:23552
	global_load_lds_dwordx4 v134, s[0:1]
	s_mov_b32 m0, s31
	ds_read_b128 v[212:215], v154 offset:22528
	global_load_lds_dwordx4 v128, s[40:41]
	s_mov_b32 m0, s35
	ds_read_b128 v[208:211], v154 offset:21504
	global_load_lds_dwordx4 v132, s[40:41]
	s_waitcnt vmcnt(8)
	s_waitcnt lgkmcnt(0)
	s_setprio 3
	s_barrier
	v_mfma_f32_16x16x32_bf16 v[60:63], v[156:159], v[188:191], v[60:63]
	v_mfma_f32_16x16x32_bf16 v[56:59], v[164:167], v[188:191], v[56:59]
	v_mfma_f32_16x16x32_bf16 v[44:47], v[156:159], v[196:199], v[44:47]
	v_mfma_f32_16x16x32_bf16 v[40:43], v[164:167], v[196:199], v[40:43]
	v_mfma_f32_16x16x32_bf16 v[28:31], v[156:159], v[204:207], v[28:31]
	v_mfma_f32_16x16x32_bf16 v[24:27], v[164:167], v[204:207], v[24:27]
	v_mfma_f32_16x16x32_bf16 v[12:15], v[156:159], v[212:215], v[12:15]
	v_mfma_f32_16x16x32_bf16 v[8:11], v[164:167], v[212:215], v[8:11]
	v_mfma_f32_16x16x32_bf16 v[60:63], v[160:163], v[192:195], v[60:63]
	v_mfma_f32_16x16x32_bf16 v[56:59], v[168:171], v[192:195], v[56:59]
	v_mfma_f32_16x16x32_bf16 v[44:47], v[160:163], v[200:203], v[44:47]
	v_mfma_f32_16x16x32_bf16 v[40:43], v[168:171], v[200:203], v[40:43]
	v_mfma_f32_16x16x32_bf16 v[28:31], v[160:163], v[208:211], v[28:31]
	v_mfma_f32_16x16x32_bf16 v[24:27], v[168:171], v[208:211], v[24:27]
	v_mfma_f32_16x16x32_bf16 v[12:15], v[160:163], v[216:219], v[12:15]
	v_mfma_f32_16x16x32_bf16 v[8:11], v[168:171], v[216:219], v[8:11]
	s_setprio 0
	s_setprio 3
	v_mfma_f32_16x16x32_bf16 v[52:55], v[172:175], v[188:191], v[52:55]
	v_mfma_f32_16x16x32_bf16 v[48:51], v[180:183], v[188:191], v[48:51]
	v_mfma_f32_16x16x32_bf16 v[36:39], v[172:175], v[196:199], v[36:39]
	v_mfma_f32_16x16x32_bf16 v[32:35], v[180:183], v[196:199], v[32:35]
	v_mfma_f32_16x16x32_bf16 v[20:23], v[172:175], v[204:207], v[20:23]
	v_mfma_f32_16x16x32_bf16 v[16:19], v[180:183], v[204:207], v[16:19]
	v_mfma_f32_16x16x32_bf16 v[4:7], v[172:175], v[212:215], v[4:7]
	v_mfma_f32_16x16x32_bf16 v[0:3], v[180:183], v[212:215], v[0:3]
	v_mfma_f32_16x16x32_bf16 v[52:55], v[176:179], v[192:195], v[52:55]
	v_mfma_f32_16x16x32_bf16 v[48:51], v[184:187], v[192:195], v[48:51]
	v_mfma_f32_16x16x32_bf16 v[36:39], v[176:179], v[200:203], v[36:39]
	v_mfma_f32_16x16x32_bf16 v[32:35], v[184:187], v[200:203], v[32:35]
	v_mfma_f32_16x16x32_bf16 v[20:23], v[176:179], v[208:211], v[20:23]
	v_mfma_f32_16x16x32_bf16 v[16:19], v[184:187], v[208:211], v[16:19]
	v_mfma_f32_16x16x32_bf16 v[4:7], v[176:179], v[216:219], v[4:7]
	v_mfma_f32_16x16x32_bf16 v[0:3], v[184:187], v[216:219], v[0:3]
	s_barrier
	s_setprio 0
	s_add_i32 s62, 0, 0x18000
	s_add_i32 s63, 0, 0x1c000
	ds_read_b128 v[156:159], v226
	ds_read_b128 v[160:163], v226 offset:1024
	ds_read_b128 v[164:167], v226 offset:2048
	ds_read_b128 v[168:171], v226 offset:3072
	ds_read_b128 v[172:175], v227
	ds_read_b128 v[176:179], v227 offset:1024
	ds_read_b128 v[180:183], v227 offset:2048
	ds_read_b128 v[184:187], v227 offset:3072
	s_add_u32 s0, s40, 0x100000
	s_addc_u32 s1, s41, 0
	s_mov_b32 m0, s44
	ds_read_b128 v[188:191], v154 offset:32768
	ds_read_b128 v[192:195], v154 offset:33792
	ds_read_b128 v[196:199], v154 offset:34816
	ds_read_b128 v[200:203], v154 offset:35840
	ds_read_b128 v[204:207], v154 offset:36864
	ds_read_b128 v[208:211], v154 offset:37888
	ds_read_b128 v[212:215], v154 offset:38912
	global_load_lds_dwordx4 v128, s[0:1]
	s_mov_b32 m0, s45
	ds_read_b128 v[216:219], v154 offset:39936
	global_load_lds_dwordx4 v132, s[0:1]
	s_waitcnt vmcnt(8)
	s_waitcnt lgkmcnt(0)
	s_setprio 3
	s_barrier
	v_mfma_f32_16x16x32_bf16 v[124:127], v[156:159], v[188:191], v[124:127]
	v_mfma_f32_16x16x32_bf16 v[120:123], v[164:167], v[188:191], v[120:123]
	v_mfma_f32_16x16x32_bf16 v[108:111], v[156:159], v[196:199], v[108:111]
	v_mfma_f32_16x16x32_bf16 v[104:107], v[164:167], v[196:199], v[104:107]
	v_mfma_f32_16x16x32_bf16 v[92:95], v[156:159], v[204:207], v[92:95]
	v_mfma_f32_16x16x32_bf16 v[88:91], v[164:167], v[204:207], v[88:91]
	v_mfma_f32_16x16x32_bf16 v[76:79], v[156:159], v[212:215], v[76:79]
	v_mfma_f32_16x16x32_bf16 v[72:75], v[164:167], v[212:215], v[72:75]
	v_mfma_f32_16x16x32_bf16 v[124:127], v[160:163], v[192:195], v[124:127]
	v_mfma_f32_16x16x32_bf16 v[120:123], v[168:171], v[192:195], v[120:123]
	v_mfma_f32_16x16x32_bf16 v[108:111], v[160:163], v[200:203], v[108:111]
	v_mfma_f32_16x16x32_bf16 v[104:107], v[168:171], v[200:203], v[104:107]
	v_mfma_f32_16x16x32_bf16 v[92:95], v[160:163], v[208:211], v[92:95]
	v_mfma_f32_16x16x32_bf16 v[88:91], v[168:171], v[208:211], v[88:91]
	v_mfma_f32_16x16x32_bf16 v[76:79], v[160:163], v[216:219], v[76:79]
	v_mfma_f32_16x16x32_bf16 v[72:75], v[168:171], v[216:219], v[72:75]
	s_setprio 0
	s_setprio 3
	v_mfma_f32_16x16x32_bf16 v[116:119], v[172:175], v[188:191], v[116:119]
	v_mfma_f32_16x16x32_bf16 v[112:115], v[180:183], v[188:191], v[112:115]
	v_mfma_f32_16x16x32_bf16 v[100:103], v[172:175], v[196:199], v[100:103]
	v_mfma_f32_16x16x32_bf16 v[96:99], v[180:183], v[196:199], v[96:99]
	v_mfma_f32_16x16x32_bf16 v[84:87], v[172:175], v[204:207], v[84:87]
	v_mfma_f32_16x16x32_bf16 v[80:83], v[180:183], v[204:207], v[80:83]
	v_mfma_f32_16x16x32_bf16 v[68:71], v[172:175], v[212:215], v[68:71]
	v_mfma_f32_16x16x32_bf16 v[64:67], v[180:183], v[212:215], v[64:67]
	v_mfma_f32_16x16x32_bf16 v[116:119], v[176:179], v[192:195], v[116:119]
	v_mfma_f32_16x16x32_bf16 v[112:115], v[184:187], v[192:195], v[112:115]
	v_mfma_f32_16x16x32_bf16 v[100:103], v[176:179], v[200:203], v[100:103]
	v_mfma_f32_16x16x32_bf16 v[96:99], v[184:187], v[200:203], v[96:99]
	v_mfma_f32_16x16x32_bf16 v[84:87], v[176:179], v[208:211], v[84:87]
	v_mfma_f32_16x16x32_bf16 v[80:83], v[184:187], v[208:211], v[80:83]
	v_mfma_f32_16x16x32_bf16 v[68:71], v[176:179], v[216:219], v[68:71]
	v_mfma_f32_16x16x32_bf16 v[64:67], v[184:187], v[216:219], v[64:67]
	s_barrier
	s_setprio 0
	s_add_i32 s0, s62, s43
	s_add_u32 s100, s38, 0x80
	s_addc_u32 s101, s39, 0
	s_mov_b32 m0, s0
	ds_read_b128 v[188:191], v154 offset:49152
	ds_read_b128 v[192:195], v154 offset:50176
	ds_read_b128 v[196:199], v154 offset:51200
	ds_read_b128 v[200:203], v154 offset:52224
	global_load_lds_dwordx4 v130, s[100:101]
	s_add_i32 m0, s0, 0x2000
	s_add_u32 s0, s38, 0x100080
	s_addc_u32 s1, s39, 0
	s_add_i32 s38, s63, s43
	global_load_lds_dwordx4 v134, s[100:101]
	s_mov_b32 m0, s38
	ds_read_b128 v[216:219], v154 offset:56320
	global_load_lds_dwordx4 v130, s[0:1]
	s_add_i32 m0, s38, 0x2000
	ds_read_b128 v[212:215], v154 offset:55296
	global_load_lds_dwordx4 v134, s[0:1]
	s_add_u32 s100, s40, 0x80
	s_addc_u32 s101, s41, 0
	s_mov_b32 m0, s46
	ds_read_b128 v[208:211], v154 offset:54272
	global_load_lds_dwordx4 v128, s[100:101]
	s_mov_b32 m0, s47
	ds_read_b128 v[204:207], v154 offset:53248
	global_load_lds_dwordx4 v132, s[100:101]
	s_waitcnt vmcnt(8)
	s_waitcnt lgkmcnt(0)
	s_setprio 3
	s_barrier
	v_mfma_f32_16x16x32_bf16 v[60:63], v[156:159], v[188:191], v[60:63]
	v_mfma_f32_16x16x32_bf16 v[56:59], v[164:167], v[188:191], v[56:59]
	v_mfma_f32_16x16x32_bf16 v[44:47], v[156:159], v[196:199], v[44:47]
	v_mfma_f32_16x16x32_bf16 v[40:43], v[164:167], v[196:199], v[40:43]
	v_mfma_f32_16x16x32_bf16 v[28:31], v[156:159], v[204:207], v[28:31]
	v_mfma_f32_16x16x32_bf16 v[24:27], v[164:167], v[204:207], v[24:27]
	v_mfma_f32_16x16x32_bf16 v[12:15], v[156:159], v[212:215], v[12:15]
	v_mfma_f32_16x16x32_bf16 v[8:11], v[164:167], v[212:215], v[8:11]
	v_mfma_f32_16x16x32_bf16 v[60:63], v[160:163], v[192:195], v[60:63]
	v_mfma_f32_16x16x32_bf16 v[56:59], v[168:171], v[192:195], v[56:59]
	v_mfma_f32_16x16x32_bf16 v[44:47], v[160:163], v[200:203], v[44:47]
	v_mfma_f32_16x16x32_bf16 v[40:43], v[168:171], v[200:203], v[40:43]
	v_mfma_f32_16x16x32_bf16 v[28:31], v[160:163], v[208:211], v[28:31]
	v_mfma_f32_16x16x32_bf16 v[24:27], v[168:171], v[208:211], v[24:27]
	v_mfma_f32_16x16x32_bf16 v[12:15], v[160:163], v[216:219], v[12:15]
	v_mfma_f32_16x16x32_bf16 v[8:11], v[168:171], v[216:219], v[8:11]
	s_setprio 0
	s_setprio 3
	v_mfma_f32_16x16x32_bf16 v[52:55], v[172:175], v[188:191], v[52:55]
	v_mfma_f32_16x16x32_bf16 v[48:51], v[180:183], v[188:191], v[48:51]
	v_mfma_f32_16x16x32_bf16 v[36:39], v[172:175], v[196:199], v[36:39]
	v_mfma_f32_16x16x32_bf16 v[32:35], v[180:183], v[196:199], v[32:35]
	v_mfma_f32_16x16x32_bf16 v[20:23], v[172:175], v[204:207], v[20:23]
	v_mfma_f32_16x16x32_bf16 v[16:19], v[180:183], v[204:207], v[16:19]
	v_mfma_f32_16x16x32_bf16 v[4:7], v[172:175], v[212:215], v[4:7]
	v_mfma_f32_16x16x32_bf16 v[0:3], v[180:183], v[212:215], v[0:3]
	v_mfma_f32_16x16x32_bf16 v[52:55], v[176:179], v[192:195], v[52:55]
	v_mfma_f32_16x16x32_bf16 v[48:51], v[184:187], v[192:195], v[48:51]
	v_mfma_f32_16x16x32_bf16 v[36:39], v[176:179], v[200:203], v[36:39]
	v_mfma_f32_16x16x32_bf16 v[32:35], v[184:187], v[200:203], v[32:35]
	v_mfma_f32_16x16x32_bf16 v[20:23], v[176:179], v[208:211], v[20:23]
	v_mfma_f32_16x16x32_bf16 v[16:19], v[184:187], v[208:211], v[16:19]
	v_mfma_f32_16x16x32_bf16 v[4:7], v[176:179], v[216:219], v[4:7]
	v_mfma_f32_16x16x32_bf16 v[0:3], v[184:187], v[216:219], v[0:3]
	s_barrier
	s_setprio 0
	s_add_u32 s36, s36, 0x100
	s_addc_u32 s37, s37, 0
	s_add_i32 s61, s61, 2
	s_add_u32 s59, s59, 0x100
	s_addc_u32 s60, s60, 0
	s_cmp_gt_u32 s61, 61
	s_cbranch_scc0 .LBB0_677
	s_and_b64 vcc, exec, s[12:13]
	s_cbranch_vccz .LBB0_680
	s_barrier

.LBB0_705:
	ds_read_b128 v[24:27], v191
	ds_read_b128 v[28:31], v191 offset:1024
	ds_read_b128 v[16:19], v191 offset:2048
	ds_read_b128 v[20:23], v191 offset:3072
	ds_read_b128 v[8:11], v192
	ds_read_b128 v[12:15], v192 offset:1024
	ds_read_b128 v[0:3], v192 offset:2048
	ds_read_b128 v[4:7], v192 offset:3072
	s_add_u32 s0, s44, 0xfff80080
	s_addc_u32 s1, s45, -1
	s_cmp_eq_u32 s70, 28
	s_cselect_b32 s49, s60, s1
	s_cselect_b32 s48, s66, s0
	s_cselect_b32 s47, s31, s69
	s_cselect_b32 s46, s67, s68
	s_add_i32 m0, s41, 0xc000
	ds_read_b128 v[178:181], v193
	ds_read_b128 v[182:185], v193 offset:1024
	ds_read_b128 v[194:197], v193 offset:2048
	ds_read_b128 v[198:201], v193 offset:3072
	ds_read_b128 v[208:211], v193 offset:4096
	ds_read_b128 v[212:215], v193 offset:5120
	ds_read_b128 v[216:219], v193 offset:6144
	global_load_lds_dwordx4 v170, s[44:45]
	s_add_i32 m0, s41, 0xe000
	ds_read_b128 v[220:223], v193 offset:7168
	global_load_lds_dwordx4 v172, s[44:45]
	s_waitcnt vmcnt(8)
	s_waitcnt lgkmcnt(0)
	s_setprio 3
	s_barrier
	v_mfma_scale_f32_16x16x128_f8f6f4 v[156:159], v[24:31], v[178:185], v[156:159], v186, v186 op_sel_hi:[0,0,0]
	v_mfma_scale_f32_16x16x128_f8f6f4 v[152:155], v[16:23], v[178:185], v[152:155], v186, v186 op_sel_hi:[0,0,0]
	v_mfma_scale_f32_16x16x128_f8f6f4 v[140:143], v[24:31], v[194:201], v[140:143], v186, v186 op_sel_hi:[0,0,0]
	v_mfma_scale_f32_16x16x128_f8f6f4 v[136:139], v[16:23], v[194:201], v[136:139], v186, v186 op_sel_hi:[0,0,0]
	v_mfma_scale_f32_16x16x128_f8f6f4 v[124:127], v[24:31], v[208:215], v[124:127], v186, v186 op_sel_hi:[0,0,0]
	v_mfma_scale_f32_16x16x128_f8f6f4 v[120:123], v[16:23], v[208:215], v[120:123], v186, v186 op_sel_hi:[0,0,0]
	v_mfma_scale_f32_16x16x128_f8f6f4 v[108:111], v[24:31], v[216:223], v[108:111], v186, v186 op_sel_hi:[0,0,0]
	v_mfma_scale_f32_16x16x128_f8f6f4 v[104:107], v[16:23], v[216:223], v[104:107], v186, v186 op_sel_hi:[0,0,0]
	s_setprio 0
	s_setprio 3
	v_mfma_scale_f32_16x16x128_f8f6f4 v[148:151], v[8:15], v[178:185], v[148:151], v186, v186 op_sel_hi:[0,0,0]
	v_mfma_scale_f32_16x16x128_f8f6f4 v[144:147], v[0:7], v[178:185], v[144:147], v186, v186 op_sel_hi:[0,0,0]
	v_mfma_scale_f32_16x16x128_f8f6f4 v[132:135], v[8:15], v[194:201], v[132:135], v186, v186 op_sel_hi:[0,0,0]
	v_mfma_scale_f32_16x16x128_f8f6f4 v[128:131], v[0:7], v[194:201], v[128:131], v186, v186 op_sel_hi:[0,0,0]
	v_mfma_scale_f32_16x16x128_f8f6f4 v[116:119], v[8:15], v[208:215], v[116:119], v186, v186 op_sel_hi:[0,0,0]
	v_mfma_scale_f32_16x16x128_f8f6f4 v[112:115], v[0:7], v[208:215], v[112:115], v186, v186 op_sel_hi:[0,0,0]
	v_mfma_scale_f32_16x16x128_f8f6f4 v[100:103], v[8:15], v[216:223], v[100:103], v186, v186 op_sel_hi:[0,0,0]
	v_mfma_scale_f32_16x16x128_f8f6f4 v[96:99], v[0:7], v[216:223], v[96:99], v186, v186 op_sel_hi:[0,0,0]
	s_barrier
	s_setprio 0
	s_add_i32 s0, s58, s51
	s_mov_b32 m0, s0
	ds_read_b128 v[194:197], v193 offset:16384
	ds_read_b128 v[198:201], v193 offset:17408
	ds_read_b128 v[208:211], v193 offset:18432
	ds_read_b128 v[212:215], v193 offset:19456
	ds_read_b128 v[216:219], v193 offset:20480
	global_load_lds_dwordx4 v162, s[46:47]
	s_add_i32 m0, s0, 0x2000
	s_add_u32 s0, s46, 0x80000
	s_addc_u32 s1, s47, 0
	s_add_i32 s71, s59, s51
	global_load_lds_dwordx4 v166, s[46:47]
	s_mov_b32 m0, s71
	s_nop 0
	global_load_lds_dwordx4 v162, s[0:1]
	s_add_i32 m0, s71, 0x2000
	ds_read_b128 v[228:231], v193 offset:23552
	global_load_lds_dwordx4 v166, s[0:1]
	s_mov_b32 m0, s41
	ds_read_b128 v[224:227], v193 offset:22528
	global_load_lds_dwordx4 v160, s[48:49]
	s_mov_b32 m0, s43
	ds_read_b128 v[220:223], v193 offset:21504
	global_load_lds_dwordx4 v164, s[48:49]
	s_waitcnt vmcnt(8)
	s_waitcnt lgkmcnt(0)
	s_setprio 3
	s_barrier
	v_mfma_scale_f32_16x16x128_f8f6f4 v[92:95], v[24:31], v[194:201], v[92:95], v186, v186 op_sel_hi:[0,0,0]
	v_mfma_scale_f32_16x16x128_f8f6f4 v[88:91], v[16:23], v[194:201], v[88:91], v186, v186 op_sel_hi:[0,0,0]
	v_mfma_scale_f32_16x16x128_f8f6f4 v[80:83], v[24:31], v[208:215], v[80:83], v186, v186 op_sel_hi:[0,0,0]
	v_mfma_scale_f32_16x16x128_f8f6f4 v[72:75], v[16:23], v[208:215], v[72:75], v186, v186 op_sel_hi:[0,0,0]
	v_mfma_scale_f32_16x16x128_f8f6f4 v[64:67], v[24:31], v[216:223], v[64:67], v186, v186 op_sel_hi:[0,0,0]
	v_mfma_scale_f32_16x16x128_f8f6f4 v[56:59], v[16:23], v[216:223], v[56:59], v186, v186 op_sel_hi:[0,0,0]
	v_mfma_scale_f32_16x16x128_f8f6f4 v[48:51], v[24:31], v[224:231], v[48:51], v186, v186 op_sel_hi:[0,0,0]
	v_mfma_scale_f32_16x16x128_f8f6f4 v[40:43], v[16:23], v[224:231], v[40:43], v186, v186 op_sel_hi:[0,0,0]
	s_setprio 0
	s_setprio 3
	v_mfma_scale_f32_16x16x128_f8f6f4 v[84:87], v[8:15], v[194:201], v[84:87], v186, v186 op_sel_hi:[0,0,0]
	v_mfma_scale_f32_16x16x128_f8f6f4 v[76:79], v[0:7], v[194:201], v[76:79], v186, v186 op_sel_hi:[0,0,0]
	v_mfma_scale_f32_16x16x128_f8f6f4 v[68:71], v[8:15], v[208:215], v[68:71], v186, v186 op_sel_hi:[0,0,0]
	v_mfma_scale_f32_16x16x128_f8f6f4 v[60:63], v[0:7], v[208:215], v[60:63], v186, v186 op_sel_hi:[0,0,0]
	v_mfma_scale_f32_16x16x128_f8f6f4 v[52:55], v[8:15], v[216:223], v[52:55], v186, v186 op_sel_hi:[0,0,0]
	v_mfma_scale_f32_16x16x128_f8f6f4 v[44:47], v[0:7], v[216:223], v[44:47], v186, v186 op_sel_hi:[0,0,0]
	v_mfma_scale_f32_16x16x128_f8f6f4 v[36:39], v[8:15], v[224:231], v[36:39], v186, v186 op_sel_hi:[0,0,0]
	v_mfma_scale_f32_16x16x128_f8f6f4 v[32:35], v[0:7], v[224:231], v[32:35], v186, v186 op_sel_hi:[0,0,0]
	s_barrier
	s_setprio 0
	s_add_i32 s71, 0, 0x18000
	s_add_i32 s73, 0, 0x1c000
	ds_read_b128 v[0:3], v202
	ds_read_b128 v[4:7], v202 offset:1024
	ds_read_b128 v[8:11], v202 offset:2048
	ds_read_b128 v[12:15], v202 offset:3072
	ds_read_b128 v[16:19], v203
	ds_read_b128 v[20:23], v203 offset:1024
	ds_read_b128 v[24:27], v203 offset:2048
	ds_read_b128 v[28:31], v203 offset:3072
	s_add_u32 s0, s48, 0x80000
	s_addc_u32 s1, s49, 0
	s_mov_b32 m0, s52
	ds_read_b128 v[194:197], v193 offset:32768
	ds_read_b128 v[198:201], v193 offset:33792
	ds_read_b128 v[208:211], v193 offset:34816
	ds_read_b128 v[212:215], v193 offset:35840
	ds_read_b128 v[216:219], v193 offset:36864
	ds_read_b128 v[220:223], v193 offset:37888
	ds_read_b128 v[224:227], v193 offset:38912
	global_load_lds_dwordx4 v160, s[0:1]
	s_mov_b32 m0, s53
	ds_read_b128 v[228:231], v193 offset:39936
	global_load_lds_dwordx4 v164, s[0:1]
	s_waitcnt vmcnt(8)
	s_waitcnt lgkmcnt(0)
	s_setprio 3
	s_barrier
	v_mfma_scale_f32_16x16x128_f8f6f4 v[156:159], v[0:7], v[194:201], v[156:159], v186, v186 op_sel_hi:[0,0,0]
	v_mfma_scale_f32_16x16x128_f8f6f4 v[152:155], v[8:15], v[194:201], v[152:155], v186, v186 op_sel_hi:[0,0,0]
	v_mfma_scale_f32_16x16x128_f8f6f4 v[140:143], v[0:7], v[208:215], v[140:143], v186, v186 op_sel_hi:[0,0,0]
	v_mfma_scale_f32_16x16x128_f8f6f4 v[136:139], v[8:15], v[208:215], v[136:139], v186, v186 op_sel_hi:[0,0,0]
	v_mfma_scale_f32_16x16x128_f8f6f4 v[124:127], v[0:7], v[216:223], v[124:127], v186, v186 op_sel_hi:[0,0,0]
	v_mfma_scale_f32_16x16x128_f8f6f4 v[120:123], v[8:15], v[216:223], v[120:123], v186, v186 op_sel_hi:[0,0,0]
	v_mfma_scale_f32_16x16x128_f8f6f4 v[108:111], v[0:7], v[224:231], v[108:111], v186, v186 op_sel_hi:[0,0,0]
	v_mfma_scale_f32_16x16x128_f8f6f4 v[104:107], v[8:15], v[224:231], v[104:107], v186, v186 op_sel_hi:[0,0,0]
	s_setprio 0
	s_setprio 3
	v_mfma_scale_f32_16x16x128_f8f6f4 v[148:151], v[16:23], v[194:201], v[148:151], v186, v186 op_sel_hi:[0,0,0]
	v_mfma_scale_f32_16x16x128_f8f6f4 v[144:147], v[24:31], v[194:201], v[144:147], v186, v186 op_sel_hi:[0,0,0]
	v_mfma_scale_f32_16x16x128_f8f6f4 v[132:135], v[16:23], v[208:215], v[132:135], v186, v186 op_sel_hi:[0,0,0]
	v_mfma_scale_f32_16x16x128_f8f6f4 v[128:131], v[24:31], v[208:215], v[128:131], v186, v186 op_sel_hi:[0,0,0]
	v_mfma_scale_f32_16x16x128_f8f6f4 v[116:119], v[16:23], v[216:223], v[116:119], v186, v186 op_sel_hi:[0,0,0]
	v_mfma_scale_f32_16x16x128_f8f6f4 v[112:115], v[24:31], v[216:223], v[112:115], v186, v186 op_sel_hi:[0,0,0]
	v_mfma_scale_f32_16x16x128_f8f6f4 v[100:103], v[16:23], v[224:231], v[100:103], v186, v186 op_sel_hi:[0,0,0]
	v_mfma_scale_f32_16x16x128_f8f6f4 v[96:99], v[24:31], v[224:231], v[96:99], v186, v186 op_sel_hi:[0,0,0]
	s_barrier
	s_setprio 0
	s_add_i32 s0, s71, s51
	s_add_u32 s100, s46, 0x80
	s_addc_u32 s101, s47, 0
	s_mov_b32 m0, s0
	ds_read_b128 v[194:197], v193 offset:49152
	ds_read_b128 v[198:201], v193 offset:50176
	ds_read_b128 v[208:211], v193 offset:51200
	ds_read_b128 v[212:215], v193 offset:52224
	global_load_lds_dwordx4 v162, s[100:101]
	s_add_i32 m0, s0, 0x2000
	s_add_u32 s0, s46, 0x80080
	s_addc_u32 s1, s47, 0
	s_add_i32 s46, s73, s51
	global_load_lds_dwordx4 v166, s[100:101]
	s_mov_b32 m0, s46
	ds_read_b128 v[228:231], v193 offset:56320
	global_load_lds_dwordx4 v162, s[0:1]
	s_add_i32 m0, s46, 0x2000
	ds_read_b128 v[224:227], v193 offset:55296
	global_load_lds_dwordx4 v166, s[0:1]
	s_add_u32 s100, s48, 0x80
	s_addc_u32 s101, s49, 0
	s_mov_b32 m0, s55
	ds_read_b128 v[220:223], v193 offset:54272
	global_load_lds_dwordx4 v160, s[100:101]
	s_mov_b32 m0, s56
	ds_read_b128 v[216:219], v193 offset:53248
	global_load_lds_dwordx4 v164, s[100:101]
	s_waitcnt vmcnt(8)
	s_waitcnt lgkmcnt(0)
	s_setprio 3
	s_barrier
	v_mfma_scale_f32_16x16x128_f8f6f4 v[92:95], v[0:7], v[194:201], v[92:95], v186, v186 op_sel_hi:[0,0,0]
	v_mfma_scale_f32_16x16x128_f8f6f4 v[88:91], v[8:15], v[194:201], v[88:91], v186, v186 op_sel_hi:[0,0,0]
	v_mfma_scale_f32_16x16x128_f8f6f4 v[80:83], v[0:7], v[208:215], v[80:83], v186, v186 op_sel_hi:[0,0,0]
	v_mfma_scale_f32_16x16x128_f8f6f4 v[72:75], v[8:15], v[208:215], v[72:75], v186, v186 op_sel_hi:[0,0,0]
	v_mfma_scale_f32_16x16x128_f8f6f4 v[64:67], v[0:7], v[216:223], v[64:67], v186, v186 op_sel_hi:[0,0,0]
	v_mfma_scale_f32_16x16x128_f8f6f4 v[56:59], v[8:15], v[216:223], v[56:59], v186, v186 op_sel_hi:[0,0,0]
	v_mfma_scale_f32_16x16x128_f8f6f4 v[48:51], v[0:7], v[224:231], v[48:51], v186, v186 op_sel_hi:[0,0,0]
	v_mfma_scale_f32_16x16x128_f8f6f4 v[40:43], v[8:15], v[224:231], v[40:43], v186, v186 op_sel_hi:[0,0,0]
	s_setprio 0
	s_setprio 3
	v_mfma_scale_f32_16x16x128_f8f6f4 v[84:87], v[16:23], v[194:201], v[84:87], v186, v186 op_sel_hi:[0,0,0]
	v_mfma_scale_f32_16x16x128_f8f6f4 v[76:79], v[24:31], v[194:201], v[76:79], v186, v186 op_sel_hi:[0,0,0]
	v_mfma_scale_f32_16x16x128_f8f6f4 v[68:71], v[16:23], v[208:215], v[68:71], v186, v186 op_sel_hi:[0,0,0]
	v_mfma_scale_f32_16x16x128_f8f6f4 v[60:63], v[24:31], v[208:215], v[60:63], v186, v186 op_sel_hi:[0,0,0]
	v_mfma_scale_f32_16x16x128_f8f6f4 v[52:55], v[16:23], v[216:223], v[52:55], v186, v186 op_sel_hi:[0,0,0]
	v_mfma_scale_f32_16x16x128_f8f6f4 v[44:47], v[24:31], v[216:223], v[44:47], v186, v186 op_sel_hi:[0,0,0]
	v_mfma_scale_f32_16x16x128_f8f6f4 v[36:39], v[16:23], v[224:231], v[36:39], v186, v186 op_sel_hi:[0,0,0]
	v_mfma_scale_f32_16x16x128_f8f6f4 v[32:35], v[24:31], v[224:231], v[32:35], v186, v186 op_sel_hi:[0,0,0]
	s_barrier
	s_setprio 0
	s_add_u32 s44, s44, 0x100
	s_addc_u32 s45, s45, 0
	s_add_i32 s70, s70, 2
	s_add_u32 s68, s68, 0x100
	s_addc_u32 s69, s69, 0
	s_cmp_gt_u32 s70, 29
	s_cbranch_scc0 .LBB0_705
	s_and_b64 vcc, exec, s[12:13]
	s_cbranch_vccz .LBB0_708
	s_barrier

.LBB0_1637:
	ds_read_b128 v[152:155], v149
	ds_read_b128 v[156:159], v149 offset:1024
	ds_read_b128 v[160:163], v149 offset:2048
	ds_read_b128 v[164:167], v149 offset:3072
	ds_read_b128 v[168:171], v150
	ds_read_b128 v[172:175], v150 offset:1024
	ds_read_b128 v[176:179], v150 offset:2048
	ds_read_b128 v[180:183], v150 offset:3072
	s_add_u32 s0, s42, 0xfff00080
	s_addc_u32 s1, s43, -1
	s_cmp_eq_u32 s68, 60
	s_cselect_b32 s47, s35, s1
	s_cselect_b32 s46, s64, s0
	s_cselect_b32 s45, s31, s67
	s_cselect_b32 s44, s65, s66
	s_add_i32 m0, s41, 0xc000
	ds_read_b128 v[184:187], v151
	ds_read_b128 v[188:191], v151 offset:1024
	ds_read_b128 v[192:195], v151 offset:2048
	ds_read_b128 v[196:199], v151 offset:3072
	ds_read_b128 v[200:203], v151 offset:4096
	ds_read_b128 v[210:213], v151 offset:5120
	ds_read_b128 v[214:217], v151 offset:6144
	global_load_lds_dwordx4 v136, s[42:43]
	s_add_i32 m0, s41, 0xe000
	ds_read_b128 v[218:221], v151 offset:7168
	global_load_lds_dwordx4 v138, s[42:43]
	s_waitcnt vmcnt(8)
	s_waitcnt lgkmcnt(0)
	s_setprio 3
	s_barrier
	v_mfma_f32_16x16x32_bf16 v[124:127], v[152:155], v[184:187], v[124:127]
	v_mfma_f32_16x16x32_bf16 v[120:123], v[160:163], v[184:187], v[120:123]
	v_mfma_f32_16x16x32_bf16 v[116:119], v[152:155], v[192:195], v[116:119]
	v_mfma_f32_16x16x32_bf16 v[108:111], v[160:163], v[192:195], v[108:111]
	v_mfma_f32_16x16x32_bf16 v[100:103], v[152:155], v[200:203], v[100:103]
	v_mfma_f32_16x16x32_bf16 v[92:95], v[160:163], v[200:203], v[92:95]
	v_mfma_f32_16x16x32_bf16 v[84:87], v[152:155], v[214:217], v[84:87]
	v_mfma_f32_16x16x32_bf16 v[76:79], v[160:163], v[214:217], v[76:79]
	v_mfma_f32_16x16x32_bf16 v[124:127], v[156:159], v[188:191], v[124:127]
	v_mfma_f32_16x16x32_bf16 v[120:123], v[164:167], v[188:191], v[120:123]
	v_mfma_f32_16x16x32_bf16 v[116:119], v[156:159], v[196:199], v[116:119]
	v_mfma_f32_16x16x32_bf16 v[108:111], v[164:167], v[196:199], v[108:111]
	v_mfma_f32_16x16x32_bf16 v[100:103], v[156:159], v[210:213], v[100:103]
	v_mfma_f32_16x16x32_bf16 v[92:95], v[164:167], v[210:213], v[92:95]
	v_mfma_f32_16x16x32_bf16 v[84:87], v[156:159], v[218:221], v[84:87]
	v_mfma_f32_16x16x32_bf16 v[76:79], v[164:167], v[218:221], v[76:79]
	s_setprio 0
	s_setprio 3
	v_mfma_f32_16x16x32_bf16 v[112:115], v[168:171], v[184:187], v[112:115]
	v_mfma_f32_16x16x32_bf16 v[104:107], v[176:179], v[184:187], v[104:107]
	v_mfma_f32_16x16x32_bf16 v[96:99], v[168:171], v[192:195], v[96:99]
	v_mfma_f32_16x16x32_bf16 v[88:91], v[176:179], v[192:195], v[88:91]
	v_mfma_f32_16x16x32_bf16 v[80:83], v[168:171], v[200:203], v[80:83]
	v_mfma_f32_16x16x32_bf16 v[72:75], v[176:179], v[200:203], v[72:75]
	v_mfma_f32_16x16x32_bf16 v[68:71], v[168:171], v[214:217], v[68:71]
	v_mfma_f32_16x16x32_bf16 v[64:67], v[176:179], v[214:217], v[64:67]
	v_mfma_f32_16x16x32_bf16 v[112:115], v[172:175], v[188:191], v[112:115]
	v_mfma_f32_16x16x32_bf16 v[104:107], v[180:183], v[188:191], v[104:107]
	v_mfma_f32_16x16x32_bf16 v[96:99], v[172:175], v[196:199], v[96:99]
	v_mfma_f32_16x16x32_bf16 v[88:91], v[180:183], v[196:199], v[88:91]
	v_mfma_f32_16x16x32_bf16 v[80:83], v[172:175], v[210:213], v[80:83]
	v_mfma_f32_16x16x32_bf16 v[72:75], v[180:183], v[210:213], v[72:75]
	v_mfma_f32_16x16x32_bf16 v[68:71], v[172:175], v[218:221], v[68:71]
	v_mfma_f32_16x16x32_bf16 v[64:67], v[180:183], v[218:221], v[64:67]
	s_barrier
	s_setprio 0
	s_add_i32 s0, s57, s49
	s_mov_b32 m0, s0
	ds_read_b128 v[184:187], v151 offset:16384
	ds_read_b128 v[188:191], v151 offset:17408
	ds_read_b128 v[192:195], v151 offset:18432
	ds_read_b128 v[196:199], v151 offset:19456
	ds_read_b128 v[200:203], v151 offset:20480
	global_load_lds_dwordx4 v130, s[44:45]
	s_add_i32 m0, s0, 0x2000
	s_add_u32 s0, s44, 0x100000
	s_addc_u32 s1, s45, 0
	s_add_i32 s69, s58, s49
	global_load_lds_dwordx4 v134, s[44:45]
	s_mov_b32 m0, s69
	s_nop 0
	global_load_lds_dwordx4 v130, s[0:1]
	s_add_i32 m0, s69, 0x2000
	ds_read_b128 v[218:221], v151 offset:23552
	global_load_lds_dwordx4 v134, s[0:1]
	s_mov_b32 m0, s41
	ds_read_b128 v[214:217], v151 offset:22528
	global_load_lds_dwordx4 v128, s[46:47]
	s_mov_b32 m0, s50
	ds_read_b128 v[210:213], v151 offset:21504
	global_load_lds_dwordx4 v132, s[46:47]
	s_waitcnt vmcnt(8)
	s_waitcnt lgkmcnt(0)
	s_setprio 3
	s_barrier
	v_mfma_f32_16x16x32_bf16 v[60:63], v[152:155], v[184:187], v[60:63]
	v_mfma_f32_16x16x32_bf16 v[56:59], v[160:163], v[184:187], v[56:59]
	v_mfma_f32_16x16x32_bf16 v[52:55], v[152:155], v[192:195], v[52:55]
	v_mfma_f32_16x16x32_bf16 v[44:47], v[160:163], v[192:195], v[44:47]
	v_mfma_f32_16x16x32_bf16 v[36:39], v[152:155], v[200:203], v[36:39]
	v_mfma_f32_16x16x32_bf16 v[28:31], v[160:163], v[200:203], v[28:31]
	v_mfma_f32_16x16x32_bf16 v[20:23], v[152:155], v[214:217], v[20:23]
	v_mfma_f32_16x16x32_bf16 v[12:15], v[160:163], v[214:217], v[12:15]
	v_mfma_f32_16x16x32_bf16 v[60:63], v[156:159], v[188:191], v[60:63]
	v_mfma_f32_16x16x32_bf16 v[56:59], v[164:167], v[188:191], v[56:59]
	v_mfma_f32_16x16x32_bf16 v[52:55], v[156:159], v[196:199], v[52:55]
	v_mfma_f32_16x16x32_bf16 v[44:47], v[164:167], v[196:199], v[44:47]
	v_mfma_f32_16x16x32_bf16 v[36:39], v[156:159], v[210:213], v[36:39]
	v_mfma_f32_16x16x32_bf16 v[28:31], v[164:167], v[210:213], v[28:31]
	v_mfma_f32_16x16x32_bf16 v[20:23], v[156:159], v[218:221], v[20:23]
	v_mfma_f32_16x16x32_bf16 v[12:15], v[164:167], v[218:221], v[12:15]
	s_setprio 0
	s_setprio 3
	v_mfma_f32_16x16x32_bf16 v[48:51], v[168:171], v[184:187], v[48:51]
	v_mfma_f32_16x16x32_bf16 v[40:43], v[176:179], v[184:187], v[40:43]
	v_mfma_f32_16x16x32_bf16 v[32:35], v[168:171], v[192:195], v[32:35]
	v_mfma_f32_16x16x32_bf16 v[24:27], v[176:179], v[192:195], v[24:27]
	v_mfma_f32_16x16x32_bf16 v[16:19], v[168:171], v[200:203], v[16:19]
	v_mfma_f32_16x16x32_bf16 v[8:11], v[176:179], v[200:203], v[8:11]
	v_mfma_f32_16x16x32_bf16 v[4:7], v[168:171], v[214:217], v[4:7]
	v_mfma_f32_16x16x32_bf16 v[0:3], v[176:179], v[214:217], v[0:3]
	v_mfma_f32_16x16x32_bf16 v[48:51], v[172:175], v[188:191], v[48:51]
	v_mfma_f32_16x16x32_bf16 v[40:43], v[180:183], v[188:191], v[40:43]
	v_mfma_f32_16x16x32_bf16 v[32:35], v[172:175], v[196:199], v[32:35]
	v_mfma_f32_16x16x32_bf16 v[24:27], v[180:183], v[196:199], v[24:27]
	v_mfma_f32_16x16x32_bf16 v[16:19], v[172:175], v[210:213], v[16:19]
	v_mfma_f32_16x16x32_bf16 v[8:11], v[180:183], v[210:213], v[8:11]
	v_mfma_f32_16x16x32_bf16 v[4:7], v[172:175], v[218:221], v[4:7]
	v_mfma_f32_16x16x32_bf16 v[0:3], v[180:183], v[218:221], v[0:3]
	s_barrier
	s_setprio 0
	s_add_i32 s69, 0, 0x18000
	s_add_i32 s70, 0, 0x1c000
	ds_read_b128 v[152:155], v228
	ds_read_b128 v[156:159], v228 offset:1024
	ds_read_b128 v[160:163], v228 offset:2048
	ds_read_b128 v[164:167], v228 offset:3072
	ds_read_b128 v[168:171], v229
	ds_read_b128 v[172:175], v229 offset:1024
	ds_read_b128 v[176:179], v229 offset:2048
	ds_read_b128 v[180:183], v229 offset:3072
	s_add_u32 s0, s46, 0x100000
	s_addc_u32 s1, s47, 0
	s_mov_b32 m0, s51
	ds_read_b128 v[184:187], v151 offset:32768
	ds_read_b128 v[188:191], v151 offset:33792
	ds_read_b128 v[192:195], v151 offset:34816
	ds_read_b128 v[196:199], v151 offset:35840
	ds_read_b128 v[200:203], v151 offset:36864
	ds_read_b128 v[210:213], v151 offset:37888
	ds_read_b128 v[214:217], v151 offset:38912
	global_load_lds_dwordx4 v128, s[0:1]
	s_mov_b32 m0, s52
	ds_read_b128 v[218:221], v151 offset:39936
	global_load_lds_dwordx4 v132, s[0:1]
	s_waitcnt vmcnt(8)
	s_waitcnt lgkmcnt(0)
	s_setprio 3
	s_barrier
	v_mfma_f32_16x16x32_bf16 v[124:127], v[152:155], v[184:187], v[124:127]
	v_mfma_f32_16x16x32_bf16 v[120:123], v[160:163], v[184:187], v[120:123]
	v_mfma_f32_16x16x32_bf16 v[116:119], v[152:155], v[192:195], v[116:119]
	v_mfma_f32_16x16x32_bf16 v[108:111], v[160:163], v[192:195], v[108:111]
	v_mfma_f32_16x16x32_bf16 v[100:103], v[152:155], v[200:203], v[100:103]
	v_mfma_f32_16x16x32_bf16 v[92:95], v[160:163], v[200:203], v[92:95]
	v_mfma_f32_16x16x32_bf16 v[84:87], v[152:155], v[214:217], v[84:87]
	v_mfma_f32_16x16x32_bf16 v[76:79], v[160:163], v[214:217], v[76:79]
	v_mfma_f32_16x16x32_bf16 v[124:127], v[156:159], v[188:191], v[124:127]
	v_mfma_f32_16x16x32_bf16 v[120:123], v[164:167], v[188:191], v[120:123]
	v_mfma_f32_16x16x32_bf16 v[116:119], v[156:159], v[196:199], v[116:119]
	v_mfma_f32_16x16x32_bf16 v[108:111], v[164:167], v[196:199], v[108:111]
	v_mfma_f32_16x16x32_bf16 v[100:103], v[156:159], v[210:213], v[100:103]
	v_mfma_f32_16x16x32_bf16 v[92:95], v[164:167], v[210:213], v[92:95]
	v_mfma_f32_16x16x32_bf16 v[84:87], v[156:159], v[218:221], v[84:87]
	v_mfma_f32_16x16x32_bf16 v[76:79], v[164:167], v[218:221], v[76:79]
	s_setprio 0
	s_setprio 3
	v_mfma_f32_16x16x32_bf16 v[112:115], v[168:171], v[184:187], v[112:115]
	v_mfma_f32_16x16x32_bf16 v[104:107], v[176:179], v[184:187], v[104:107]
	v_mfma_f32_16x16x32_bf16 v[96:99], v[168:171], v[192:195], v[96:99]
	v_mfma_f32_16x16x32_bf16 v[88:91], v[176:179], v[192:195], v[88:91]
	v_mfma_f32_16x16x32_bf16 v[80:83], v[168:171], v[200:203], v[80:83]
	v_mfma_f32_16x16x32_bf16 v[72:75], v[176:179], v[200:203], v[72:75]
	v_mfma_f32_16x16x32_bf16 v[68:71], v[168:171], v[214:217], v[68:71]
	v_mfma_f32_16x16x32_bf16 v[64:67], v[176:179], v[214:217], v[64:67]
	v_mfma_f32_16x16x32_bf16 v[112:115], v[172:175], v[188:191], v[112:115]
	v_mfma_f32_16x16x32_bf16 v[104:107], v[180:183], v[188:191], v[104:107]
	v_mfma_f32_16x16x32_bf16 v[96:99], v[172:175], v[196:199], v[96:99]
	v_mfma_f32_16x16x32_bf16 v[88:91], v[180:183], v[196:199], v[88:91]
	v_mfma_f32_16x16x32_bf16 v[80:83], v[172:175], v[210:213], v[80:83]
	v_mfma_f32_16x16x32_bf16 v[72:75], v[180:183], v[210:213], v[72:75]
	v_mfma_f32_16x16x32_bf16 v[68:71], v[172:175], v[218:221], v[68:71]
	v_mfma_f32_16x16x32_bf16 v[64:67], v[180:183], v[218:221], v[64:67]
	s_barrier
	s_setprio 0
	s_add_i32 s0, s69, s49
	s_add_u32 s100, s44, 0x80
	s_addc_u32 s101, s45, 0
	s_mov_b32 m0, s0
	ds_read_b128 v[184:187], v151 offset:49152
	ds_read_b128 v[188:191], v151 offset:50176
	ds_read_b128 v[192:195], v151 offset:51200
	ds_read_b128 v[196:199], v151 offset:52224
	global_load_lds_dwordx4 v130, s[100:101]
	s_add_i32 m0, s0, 0x2000
	s_add_u32 s0, s44, 0x100080
	s_addc_u32 s1, s45, 0
	s_add_i32 s44, s70, s49
	global_load_lds_dwordx4 v134, s[100:101]
	s_mov_b32 m0, s44
	ds_read_b128 v[218:221], v151 offset:56320
	global_load_lds_dwordx4 v130, s[0:1]
	s_add_i32 m0, s44, 0x2000
	ds_read_b128 v[214:217], v151 offset:55296
	global_load_lds_dwordx4 v134, s[0:1]
	s_add_u32 s100, s46, 0x80
	s_addc_u32 s101, s47, 0
	s_mov_b32 m0, s54
	ds_read_b128 v[210:213], v151 offset:54272
	global_load_lds_dwordx4 v128, s[100:101]
	s_mov_b32 m0, s55
	ds_read_b128 v[200:203], v151 offset:53248
	global_load_lds_dwordx4 v132, s[100:101]
	s_waitcnt vmcnt(8)
	s_waitcnt lgkmcnt(0)
	s_setprio 3
	s_barrier
	v_mfma_f32_16x16x32_bf16 v[60:63], v[152:155], v[184:187], v[60:63]
	v_mfma_f32_16x16x32_bf16 v[56:59], v[160:163], v[184:187], v[56:59]
	v_mfma_f32_16x16x32_bf16 v[52:55], v[152:155], v[192:195], v[52:55]
	v_mfma_f32_16x16x32_bf16 v[44:47], v[160:163], v[192:195], v[44:47]
	v_mfma_f32_16x16x32_bf16 v[36:39], v[152:155], v[200:203], v[36:39]
	v_mfma_f32_16x16x32_bf16 v[28:31], v[160:163], v[200:203], v[28:31]
	v_mfma_f32_16x16x32_bf16 v[20:23], v[152:155], v[214:217], v[20:23]
	v_mfma_f32_16x16x32_bf16 v[12:15], v[160:163], v[214:217], v[12:15]
	v_mfma_f32_16x16x32_bf16 v[60:63], v[156:159], v[188:191], v[60:63]
	v_mfma_f32_16x16x32_bf16 v[56:59], v[164:167], v[188:191], v[56:59]
	v_mfma_f32_16x16x32_bf16 v[52:55], v[156:159], v[196:199], v[52:55]
	v_mfma_f32_16x16x32_bf16 v[44:47], v[164:167], v[196:199], v[44:47]
	v_mfma_f32_16x16x32_bf16 v[36:39], v[156:159], v[210:213], v[36:39]
	v_mfma_f32_16x16x32_bf16 v[28:31], v[164:167], v[210:213], v[28:31]
	v_mfma_f32_16x16x32_bf16 v[20:23], v[156:159], v[218:221], v[20:23]
	v_mfma_f32_16x16x32_bf16 v[12:15], v[164:167], v[218:221], v[12:15]
	s_setprio 0
	s_setprio 3
	v_mfma_f32_16x16x32_bf16 v[48:51], v[168:171], v[184:187], v[48:51]
	v_mfma_f32_16x16x32_bf16 v[40:43], v[176:179], v[184:187], v[40:43]
	v_mfma_f32_16x16x32_bf16 v[32:35], v[168:171], v[192:195], v[32:35]
	v_mfma_f32_16x16x32_bf16 v[24:27], v[176:179], v[192:195], v[24:27]
	v_mfma_f32_16x16x32_bf16 v[16:19], v[168:171], v[200:203], v[16:19]
	v_mfma_f32_16x16x32_bf16 v[8:11], v[176:179], v[200:203], v[8:11]
	v_mfma_f32_16x16x32_bf16 v[4:7], v[168:171], v[214:217], v[4:7]
	v_mfma_f32_16x16x32_bf16 v[0:3], v[176:179], v[214:217], v[0:3]
	v_mfma_f32_16x16x32_bf16 v[48:51], v[172:175], v[188:191], v[48:51]
	v_mfma_f32_16x16x32_bf16 v[40:43], v[180:183], v[188:191], v[40:43]
	v_mfma_f32_16x16x32_bf16 v[32:35], v[172:175], v[196:199], v[32:35]
	v_mfma_f32_16x16x32_bf16 v[24:27], v[180:183], v[196:199], v[24:27]
	v_mfma_f32_16x16x32_bf16 v[16:19], v[172:175], v[210:213], v[16:19]
	v_mfma_f32_16x16x32_bf16 v[8:11], v[180:183], v[210:213], v[8:11]
	v_mfma_f32_16x16x32_bf16 v[4:7], v[172:175], v[218:221], v[4:7]
	v_mfma_f32_16x16x32_bf16 v[0:3], v[180:183], v[218:221], v[0:3]
	s_barrier
	s_setprio 0
	s_add_u32 s42, s42, 0x100
	s_addc_u32 s43, s43, 0
	s_add_i32 s68, s68, 2
	s_add_u32 s66, s66, 0x100
	s_addc_u32 s67, s67, 0
	s_cmp_gt_u32 s68, 61
	s_cbranch_scc0 .LBB0_1637
	s_and_b64 vcc, exec, s[16:17]
	s_cbranch_vccz .LBB0_1640
	s_barrier

.LBB0_1813:
	ds_read_b128 v[148:151], v156
	ds_read_b128 v[160:163], v156 offset:1024
	ds_read_b128 v[164:167], v156 offset:2048
	ds_read_b128 v[168:171], v156 offset:3072
	ds_read_b128 v[172:175], v157
	ds_read_b128 v[176:179], v157 offset:1024
	ds_read_b128 v[180:183], v157 offset:2048
	ds_read_b128 v[184:187], v157 offset:3072
	s_add_u32 s0, s36, 0xfff00080
	s_addc_u32 s1, s37, -1
	s_cmp_eq_u32 s64, 60
	s_cselect_b32 s41, s59, s1
	s_cselect_b32 s40, s60, s0
	s_cselect_b32 s39, s17, s63
	s_cselect_b32 s38, s61, s62
	s_add_i32 m0, s31, 0xc000
	ds_read_b128 v[188:191], v158
	ds_read_b128 v[192:195], v158 offset:1024
	ds_read_b128 v[196:199], v158 offset:2048
	ds_read_b128 v[200:203], v158 offset:3072
	ds_read_b128 v[210:213], v158 offset:4096
	ds_read_b128 v[214:217], v158 offset:5120
	ds_read_b128 v[218:221], v158 offset:6144
	global_load_lds_dwordx4 v140, s[36:37]
	s_add_i32 m0, s31, 0xe000
	ds_read_b128 v[222:225], v158 offset:7168
	global_load_lds_dwordx4 v142, s[36:37]
	s_waitcnt vmcnt(8)
	s_waitcnt lgkmcnt(0)
	s_setprio 3
	s_barrier
	v_mfma_f32_16x16x32_bf16 v[124:127], v[148:151], v[188:191], v[124:127]
	v_mfma_f32_16x16x32_bf16 v[120:123], v[164:167], v[188:191], v[120:123]
	v_mfma_f32_16x16x32_bf16 v[108:111], v[148:151], v[196:199], v[108:111]
	v_mfma_f32_16x16x32_bf16 v[104:107], v[164:167], v[196:199], v[104:107]
	v_mfma_f32_16x16x32_bf16 v[92:95], v[148:151], v[210:213], v[92:95]
	v_mfma_f32_16x16x32_bf16 v[88:91], v[164:167], v[210:213], v[88:91]
	v_mfma_f32_16x16x32_bf16 v[76:79], v[148:151], v[218:221], v[76:79]
	v_mfma_f32_16x16x32_bf16 v[72:75], v[164:167], v[218:221], v[72:75]
	v_mfma_f32_16x16x32_bf16 v[124:127], v[160:163], v[192:195], v[124:127]
	v_mfma_f32_16x16x32_bf16 v[120:123], v[168:171], v[192:195], v[120:123]
	v_mfma_f32_16x16x32_bf16 v[108:111], v[160:163], v[200:203], v[108:111]
	v_mfma_f32_16x16x32_bf16 v[104:107], v[168:171], v[200:203], v[104:107]
	v_mfma_f32_16x16x32_bf16 v[92:95], v[160:163], v[214:217], v[92:95]
	v_mfma_f32_16x16x32_bf16 v[88:91], v[168:171], v[214:217], v[88:91]
	v_mfma_f32_16x16x32_bf16 v[76:79], v[160:163], v[222:225], v[76:79]
	v_mfma_f32_16x16x32_bf16 v[72:75], v[168:171], v[222:225], v[72:75]
	s_setprio 0
	s_setprio 3
	v_mfma_f32_16x16x32_bf16 v[116:119], v[172:175], v[188:191], v[116:119]
	v_mfma_f32_16x16x32_bf16 v[112:115], v[180:183], v[188:191], v[112:115]
	v_mfma_f32_16x16x32_bf16 v[100:103], v[172:175], v[196:199], v[100:103]
	v_mfma_f32_16x16x32_bf16 v[96:99], v[180:183], v[196:199], v[96:99]
	v_mfma_f32_16x16x32_bf16 v[84:87], v[172:175], v[210:213], v[84:87]
	v_mfma_f32_16x16x32_bf16 v[80:83], v[180:183], v[210:213], v[80:83]
	v_mfma_f32_16x16x32_bf16 v[68:71], v[172:175], v[218:221], v[68:71]
	v_mfma_f32_16x16x32_bf16 v[64:67], v[180:183], v[218:221], v[64:67]
	v_mfma_f32_16x16x32_bf16 v[116:119], v[176:179], v[192:195], v[116:119]
	v_mfma_f32_16x16x32_bf16 v[112:115], v[184:187], v[192:195], v[112:115]
	v_mfma_f32_16x16x32_bf16 v[100:103], v[176:179], v[200:203], v[100:103]
	v_mfma_f32_16x16x32_bf16 v[96:99], v[184:187], v[200:203], v[96:99]
	v_mfma_f32_16x16x32_bf16 v[84:87], v[176:179], v[214:217], v[84:87]
	v_mfma_f32_16x16x32_bf16 v[80:83], v[184:187], v[214:217], v[80:83]
	v_mfma_f32_16x16x32_bf16 v[68:71], v[176:179], v[222:225], v[68:71]
	v_mfma_f32_16x16x32_bf16 v[64:67], v[184:187], v[222:225], v[64:67]
	s_barrier
	s_setprio 0
	s_add_i32 s0, s52, s43
	s_mov_b32 m0, s0
	ds_read_b128 v[188:191], v158 offset:16384
	ds_read_b128 v[192:195], v158 offset:17408
	ds_read_b128 v[196:199], v158 offset:18432
	ds_read_b128 v[200:203], v158 offset:19456
	ds_read_b128 v[210:213], v158 offset:20480
	global_load_lds_dwordx4 v132, s[38:39]
	s_add_i32 m0, s0, 0x2000
	s_add_u32 s0, s38, 0x100000
	s_addc_u32 s1, s39, 0
	s_add_i32 s65, s53, s43
	global_load_lds_dwordx4 v136, s[38:39]
	s_mov_b32 m0, s65
	s_nop 0
	global_load_lds_dwordx4 v132, s[0:1]
	s_add_i32 m0, s65, 0x2000
	ds_read_b128 v[222:225], v158 offset:23552
	global_load_lds_dwordx4 v136, s[0:1]
	s_mov_b32 m0, s31
	ds_read_b128 v[218:221], v158 offset:22528
	global_load_lds_dwordx4 v130, s[40:41]
	s_mov_b32 m0, s35
	ds_read_b128 v[214:217], v158 offset:21504
	global_load_lds_dwordx4 v134, s[40:41]
	s_waitcnt vmcnt(8)
	s_waitcnt lgkmcnt(0)
	s_setprio 3
	s_barrier
	v_mfma_f32_16x16x32_bf16 v[60:63], v[148:151], v[188:191], v[60:63]
	v_mfma_f32_16x16x32_bf16 v[56:59], v[164:167], v[188:191], v[56:59]
	v_mfma_f32_16x16x32_bf16 v[44:47], v[148:151], v[196:199], v[44:47]
	v_mfma_f32_16x16x32_bf16 v[40:43], v[164:167], v[196:199], v[40:43]
	v_mfma_f32_16x16x32_bf16 v[28:31], v[148:151], v[210:213], v[28:31]
	v_mfma_f32_16x16x32_bf16 v[24:27], v[164:167], v[210:213], v[24:27]
	v_mfma_f32_16x16x32_bf16 v[12:15], v[148:151], v[218:221], v[12:15]
	v_mfma_f32_16x16x32_bf16 v[8:11], v[164:167], v[218:221], v[8:11]
	v_mfma_f32_16x16x32_bf16 v[60:63], v[160:163], v[192:195], v[60:63]
	v_mfma_f32_16x16x32_bf16 v[56:59], v[168:171], v[192:195], v[56:59]
	v_mfma_f32_16x16x32_bf16 v[44:47], v[160:163], v[200:203], v[44:47]
	v_mfma_f32_16x16x32_bf16 v[40:43], v[168:171], v[200:203], v[40:43]
	v_mfma_f32_16x16x32_bf16 v[28:31], v[160:163], v[214:217], v[28:31]
	v_mfma_f32_16x16x32_bf16 v[24:27], v[168:171], v[214:217], v[24:27]
	v_mfma_f32_16x16x32_bf16 v[12:15], v[160:163], v[222:225], v[12:15]
	v_mfma_f32_16x16x32_bf16 v[8:11], v[168:171], v[222:225], v[8:11]
	s_setprio 0
	s_setprio 3
	v_mfma_f32_16x16x32_bf16 v[52:55], v[172:175], v[188:191], v[52:55]
	v_mfma_f32_16x16x32_bf16 v[48:51], v[180:183], v[188:191], v[48:51]
	v_mfma_f32_16x16x32_bf16 v[36:39], v[172:175], v[196:199], v[36:39]
	v_mfma_f32_16x16x32_bf16 v[32:35], v[180:183], v[196:199], v[32:35]
	v_mfma_f32_16x16x32_bf16 v[20:23], v[172:175], v[210:213], v[20:23]
	v_mfma_f32_16x16x32_bf16 v[16:19], v[180:183], v[210:213], v[16:19]
	v_mfma_f32_16x16x32_bf16 v[4:7], v[172:175], v[218:221], v[4:7]
	v_mfma_f32_16x16x32_bf16 v[0:3], v[180:183], v[218:221], v[0:3]
	v_mfma_f32_16x16x32_bf16 v[52:55], v[176:179], v[192:195], v[52:55]
	v_mfma_f32_16x16x32_bf16 v[48:51], v[184:187], v[192:195], v[48:51]
	v_mfma_f32_16x16x32_bf16 v[36:39], v[176:179], v[200:203], v[36:39]
	v_mfma_f32_16x16x32_bf16 v[32:35], v[184:187], v[200:203], v[32:35]
	v_mfma_f32_16x16x32_bf16 v[20:23], v[176:179], v[214:217], v[20:23]
	v_mfma_f32_16x16x32_bf16 v[16:19], v[184:187], v[214:217], v[16:19]
	v_mfma_f32_16x16x32_bf16 v[4:7], v[176:179], v[222:225], v[4:7]
	v_mfma_f32_16x16x32_bf16 v[0:3], v[184:187], v[222:225], v[0:3]
	s_barrier
	s_setprio 0
	s_add_i32 s65, 0, 0x18000
	s_add_i32 s66, 0, 0x1c000
	ds_read_b128 v[148:151], v234
	ds_read_b128 v[160:163], v234 offset:1024
	ds_read_b128 v[164:167], v234 offset:2048
	ds_read_b128 v[168:171], v234 offset:3072
	ds_read_b128 v[172:175], v235
	ds_read_b128 v[176:179], v235 offset:1024
	ds_read_b128 v[180:183], v235 offset:2048
	ds_read_b128 v[184:187], v235 offset:3072
	s_add_u32 s0, s40, 0x100000
	s_addc_u32 s1, s41, 0
	s_mov_b32 m0, s44
	ds_read_b128 v[188:191], v158 offset:32768
	ds_read_b128 v[192:195], v158 offset:33792
	ds_read_b128 v[196:199], v158 offset:34816
	ds_read_b128 v[200:203], v158 offset:35840
	ds_read_b128 v[210:213], v158 offset:36864
	ds_read_b128 v[214:217], v158 offset:37888
	ds_read_b128 v[218:221], v158 offset:38912
	global_load_lds_dwordx4 v130, s[0:1]
	s_mov_b32 m0, s45
	ds_read_b128 v[222:225], v158 offset:39936
	global_load_lds_dwordx4 v134, s[0:1]
	s_waitcnt vmcnt(8)
	s_waitcnt lgkmcnt(0)
	s_setprio 3
	s_barrier
	v_mfma_f32_16x16x32_bf16 v[124:127], v[148:151], v[188:191], v[124:127]
	v_mfma_f32_16x16x32_bf16 v[120:123], v[164:167], v[188:191], v[120:123]
	v_mfma_f32_16x16x32_bf16 v[108:111], v[148:151], v[196:199], v[108:111]
	v_mfma_f32_16x16x32_bf16 v[104:107], v[164:167], v[196:199], v[104:107]
	v_mfma_f32_16x16x32_bf16 v[92:95], v[148:151], v[210:213], v[92:95]
	v_mfma_f32_16x16x32_bf16 v[88:91], v[164:167], v[210:213], v[88:91]
	v_mfma_f32_16x16x32_bf16 v[76:79], v[148:151], v[218:221], v[76:79]
	v_mfma_f32_16x16x32_bf16 v[72:75], v[164:167], v[218:221], v[72:75]
	v_mfma_f32_16x16x32_bf16 v[124:127], v[160:163], v[192:195], v[124:127]
	v_mfma_f32_16x16x32_bf16 v[120:123], v[168:171], v[192:195], v[120:123]
	v_mfma_f32_16x16x32_bf16 v[108:111], v[160:163], v[200:203], v[108:111]
	v_mfma_f32_16x16x32_bf16 v[104:107], v[168:171], v[200:203], v[104:107]
	v_mfma_f32_16x16x32_bf16 v[92:95], v[160:163], v[214:217], v[92:95]
	v_mfma_f32_16x16x32_bf16 v[88:91], v[168:171], v[214:217], v[88:91]
	v_mfma_f32_16x16x32_bf16 v[76:79], v[160:163], v[222:225], v[76:79]
	v_mfma_f32_16x16x32_bf16 v[72:75], v[168:171], v[222:225], v[72:75]
	s_setprio 0
	s_setprio 3
	v_mfma_f32_16x16x32_bf16 v[116:119], v[172:175], v[188:191], v[116:119]
	v_mfma_f32_16x16x32_bf16 v[112:115], v[180:183], v[188:191], v[112:115]
	v_mfma_f32_16x16x32_bf16 v[100:103], v[172:175], v[196:199], v[100:103]
	v_mfma_f32_16x16x32_bf16 v[96:99], v[180:183], v[196:199], v[96:99]
	v_mfma_f32_16x16x32_bf16 v[84:87], v[172:175], v[210:213], v[84:87]
	v_mfma_f32_16x16x32_bf16 v[80:83], v[180:183], v[210:213], v[80:83]
	v_mfma_f32_16x16x32_bf16 v[68:71], v[172:175], v[218:221], v[68:71]
	v_mfma_f32_16x16x32_bf16 v[64:67], v[180:183], v[218:221], v[64:67]
	v_mfma_f32_16x16x32_bf16 v[116:119], v[176:179], v[192:195], v[116:119]
	v_mfma_f32_16x16x32_bf16 v[112:115], v[184:187], v[192:195], v[112:115]
	v_mfma_f32_16x16x32_bf16 v[100:103], v[176:179], v[200:203], v[100:103]
	v_mfma_f32_16x16x32_bf16 v[96:99], v[184:187], v[200:203], v[96:99]
	v_mfma_f32_16x16x32_bf16 v[84:87], v[176:179], v[214:217], v[84:87]
	v_mfma_f32_16x16x32_bf16 v[80:83], v[184:187], v[214:217], v[80:83]
	v_mfma_f32_16x16x32_bf16 v[68:71], v[176:179], v[222:225], v[68:71]
	v_mfma_f32_16x16x32_bf16 v[64:67], v[184:187], v[222:225], v[64:67]
	s_barrier
	s_setprio 0
	s_add_i32 s0, s65, s43
	s_add_u32 s100, s38, 0x80
	s_addc_u32 s101, s39, 0
	s_mov_b32 m0, s0
	ds_read_b128 v[188:191], v158 offset:49152
	ds_read_b128 v[192:195], v158 offset:50176
	ds_read_b128 v[196:199], v158 offset:51200
	ds_read_b128 v[200:203], v158 offset:52224
	global_load_lds_dwordx4 v132, s[100:101]
	s_add_i32 m0, s0, 0x2000
	s_add_u32 s0, s38, 0x100080
	s_addc_u32 s1, s39, 0
	s_add_i32 s38, s66, s43
	global_load_lds_dwordx4 v136, s[100:101]
	s_mov_b32 m0, s38
	ds_read_b128 v[222:225], v158 offset:56320
	global_load_lds_dwordx4 v132, s[0:1]
	s_add_i32 m0, s38, 0x2000
	ds_read_b128 v[218:221], v158 offset:55296
	global_load_lds_dwordx4 v136, s[0:1]
	s_add_u32 s100, s40, 0x80
	s_addc_u32 s101, s41, 0
	s_mov_b32 m0, s49
	ds_read_b128 v[214:217], v158 offset:54272
	global_load_lds_dwordx4 v130, s[100:101]
	s_mov_b32 m0, s50
	ds_read_b128 v[210:213], v158 offset:53248
	global_load_lds_dwordx4 v134, s[100:101]
	s_waitcnt vmcnt(8)
	s_waitcnt lgkmcnt(0)
	s_setprio 3
	s_barrier
	v_mfma_f32_16x16x32_bf16 v[60:63], v[148:151], v[188:191], v[60:63]
	v_mfma_f32_16x16x32_bf16 v[56:59], v[164:167], v[188:191], v[56:59]
	v_mfma_f32_16x16x32_bf16 v[44:47], v[148:151], v[196:199], v[44:47]
	v_mfma_f32_16x16x32_bf16 v[40:43], v[164:167], v[196:199], v[40:43]
	v_mfma_f32_16x16x32_bf16 v[28:31], v[148:151], v[210:213], v[28:31]
	v_mfma_f32_16x16x32_bf16 v[24:27], v[164:167], v[210:213], v[24:27]
	v_mfma_f32_16x16x32_bf16 v[12:15], v[148:151], v[218:221], v[12:15]
	v_mfma_f32_16x16x32_bf16 v[8:11], v[164:167], v[218:221], v[8:11]
	v_mfma_f32_16x16x32_bf16 v[60:63], v[160:163], v[192:195], v[60:63]
	v_mfma_f32_16x16x32_bf16 v[56:59], v[168:171], v[192:195], v[56:59]
	v_mfma_f32_16x16x32_bf16 v[44:47], v[160:163], v[200:203], v[44:47]
	v_mfma_f32_16x16x32_bf16 v[40:43], v[168:171], v[200:203], v[40:43]
	v_mfma_f32_16x16x32_bf16 v[28:31], v[160:163], v[214:217], v[28:31]
	v_mfma_f32_16x16x32_bf16 v[24:27], v[168:171], v[214:217], v[24:27]
	v_mfma_f32_16x16x32_bf16 v[12:15], v[160:163], v[222:225], v[12:15]
	v_mfma_f32_16x16x32_bf16 v[8:11], v[168:171], v[222:225], v[8:11]
	s_setprio 0
	s_setprio 3
	v_mfma_f32_16x16x32_bf16 v[52:55], v[172:175], v[188:191], v[52:55]
	v_mfma_f32_16x16x32_bf16 v[48:51], v[180:183], v[188:191], v[48:51]
	v_mfma_f32_16x16x32_bf16 v[36:39], v[172:175], v[196:199], v[36:39]
	v_mfma_f32_16x16x32_bf16 v[32:35], v[180:183], v[196:199], v[32:35]
	v_mfma_f32_16x16x32_bf16 v[20:23], v[172:175], v[210:213], v[20:23]
	v_mfma_f32_16x16x32_bf16 v[16:19], v[180:183], v[210:213], v[16:19]
	v_mfma_f32_16x16x32_bf16 v[4:7], v[172:175], v[218:221], v[4:7]
	v_mfma_f32_16x16x32_bf16 v[0:3], v[180:183], v[218:221], v[0:3]
	v_mfma_f32_16x16x32_bf16 v[52:55], v[176:179], v[192:195], v[52:55]
	v_mfma_f32_16x16x32_bf16 v[48:51], v[184:187], v[192:195], v[48:51]
	v_mfma_f32_16x16x32_bf16 v[36:39], v[176:179], v[200:203], v[36:39]
	v_mfma_f32_16x16x32_bf16 v[32:35], v[184:187], v[200:203], v[32:35]
	v_mfma_f32_16x16x32_bf16 v[20:23], v[176:179], v[214:217], v[20:23]
	v_mfma_f32_16x16x32_bf16 v[16:19], v[184:187], v[214:217], v[16:19]
	v_mfma_f32_16x16x32_bf16 v[4:7], v[176:179], v[222:225], v[4:7]
	v_mfma_f32_16x16x32_bf16 v[0:3], v[184:187], v[222:225], v[0:3]
	s_barrier
	s_setprio 0
	s_add_u32 s36, s36, 0x100
	s_addc_u32 s37, s37, 0
	s_add_i32 s64, s64, 2
	s_add_u32 s62, s62, 0x100
	s_addc_u32 s63, s63, 0
	s_cmp_gt_u32 s64, 61
	s_cbranch_scc0 .LBB0_1813
	s_and_b64 vcc, exec, s[14:15]
	s_cbranch_vccz .LBB0_1816
	s_barrier

.LBB0_1833:
	ds_read_b128 v[24:27], v193
	ds_read_b128 v[28:31], v193 offset:1024
	ds_read_b128 v[16:19], v193 offset:2048
	ds_read_b128 v[20:23], v193 offset:3072
	ds_read_b128 v[8:11], v194
	ds_read_b128 v[12:15], v194 offset:1024
	ds_read_b128 v[0:3], v194 offset:2048
	ds_read_b128 v[4:7], v194 offset:3072
	s_add_u32 s0, s36, 0xfff80080
	s_addc_u32 s1, s37, -1
	s_cmp_eq_u32 s65, 28
	s_cselect_b32 s41, s26, s1
	s_cselect_b32 s40, s27, s0
	s_cselect_b32 s39, s17, s64
	s_cselect_b32 s38, s31, s63
	s_add_i32 m0, s35, 0xc000
	ds_read_b128 v[180:183], v195
	ds_read_b128 v[184:187], v195 offset:1024
	ds_read_b128 v[210:213], v195 offset:2048
	ds_read_b128 v[214:217], v195 offset:3072
	ds_read_b128 v[218:221], v195 offset:4096
	ds_read_b128 v[222:225], v195 offset:5120
	ds_read_b128 v[226:229], v195 offset:6144
	global_load_lds_dwordx4 v172, s[36:37]
	s_add_i32 m0, s35, 0xe000
	ds_read_b128 v[230:233], v195 offset:7168
	global_load_lds_dwordx4 v174, s[36:37]
	s_waitcnt vmcnt(8)
	s_waitcnt lgkmcnt(0)
	s_setprio 3
	s_barrier
	v_mfma_scale_f32_16x16x128_f8f6f4 v[152:155], v[24:31], v[180:187], v[152:155], v188, v188 op_sel_hi:[0,0,0]
	v_mfma_scale_f32_16x16x128_f8f6f4 v[148:151], v[16:23], v[180:187], v[148:151], v188, v188 op_sel_hi:[0,0,0]
	v_mfma_scale_f32_16x16x128_f8f6f4 v[140:143], v[24:31], v[210:217], v[140:143], v188, v188 op_sel_hi:[0,0,0]
	v_mfma_scale_f32_16x16x128_f8f6f4 v[132:135], v[16:23], v[210:217], v[132:135], v188, v188 op_sel_hi:[0,0,0]
	v_mfma_scale_f32_16x16x128_f8f6f4 v[124:127], v[24:31], v[218:225], v[124:127], v188, v188 op_sel_hi:[0,0,0]
	v_mfma_scale_f32_16x16x128_f8f6f4 v[120:123], v[16:23], v[218:225], v[120:123], v188, v188 op_sel_hi:[0,0,0]
	v_mfma_scale_f32_16x16x128_f8f6f4 v[108:111], v[24:31], v[226:233], v[108:111], v188, v188 op_sel_hi:[0,0,0]
	v_mfma_scale_f32_16x16x128_f8f6f4 v[100:103], v[16:23], v[226:233], v[100:103], v188, v188 op_sel_hi:[0,0,0]
	s_setprio 0
	s_setprio 3
	v_mfma_scale_f32_16x16x128_f8f6f4 v[156:159], v[8:15], v[180:187], v[156:159], v188, v188 op_sel_hi:[0,0,0]
	v_mfma_scale_f32_16x16x128_f8f6f4 v[144:147], v[0:7], v[180:187], v[144:147], v188, v188 op_sel_hi:[0,0,0]
	v_mfma_scale_f32_16x16x128_f8f6f4 v[136:139], v[8:15], v[210:217], v[136:139], v188, v188 op_sel_hi:[0,0,0]
	v_mfma_scale_f32_16x16x128_f8f6f4 v[128:131], v[0:7], v[210:217], v[128:131], v188, v188 op_sel_hi:[0,0,0]
	v_mfma_scale_f32_16x16x128_f8f6f4 v[116:119], v[8:15], v[218:225], v[116:119], v188, v188 op_sel_hi:[0,0,0]
	v_mfma_scale_f32_16x16x128_f8f6f4 v[112:115], v[0:7], v[218:225], v[112:115], v188, v188 op_sel_hi:[0,0,0]
	v_mfma_scale_f32_16x16x128_f8f6f4 v[104:107], v[8:15], v[226:233], v[104:107], v188, v188 op_sel_hi:[0,0,0]
	v_mfma_scale_f32_16x16x128_f8f6f4 v[96:99], v[0:7], v[226:233], v[96:99], v188, v188 op_sel_hi:[0,0,0]
	s_barrier
	s_setprio 0
	s_add_i32 s0, s56, s45
	s_mov_b32 m0, s0
	ds_read_b128 v[210:213], v195 offset:16384
	ds_read_b128 v[214:217], v195 offset:17408
	ds_read_b128 v[218:221], v195 offset:18432
	ds_read_b128 v[222:225], v195 offset:19456
	ds_read_b128 v[226:229], v195 offset:20480
	global_load_lds_dwordx4 v164, s[38:39]
	s_add_i32 m0, s0, 0x2000
	s_add_u32 s0, s38, 0x80000
	s_addc_u32 s1, s39, 0
	s_add_i32 s66, s57, s45
	global_load_lds_dwordx4 v168, s[38:39]
	s_mov_b32 m0, s66
	s_nop 0
	global_load_lds_dwordx4 v164, s[0:1]
	s_add_i32 m0, s66, 0x2000
	ds_read_b128 v[238:241], v195 offset:23552
	global_load_lds_dwordx4 v168, s[0:1]
	s_mov_b32 m0, s35
	ds_read_b128 v[234:237], v195 offset:22528
	global_load_lds_dwordx4 v162, s[40:41]
	s_mov_b32 m0, s46
	ds_read_b128 v[230:233], v195 offset:21504
	global_load_lds_dwordx4 v166, s[40:41]
	s_waitcnt vmcnt(8)
	s_waitcnt lgkmcnt(0)
	s_setprio 3
	s_barrier
	v_mfma_scale_f32_16x16x128_f8f6f4 v[92:95], v[24:31], v[210:217], v[92:95], v188, v188 op_sel_hi:[0,0,0]
	v_mfma_scale_f32_16x16x128_f8f6f4 v[88:91], v[16:23], v[210:217], v[88:91], v188, v188 op_sel_hi:[0,0,0]
	v_mfma_scale_f32_16x16x128_f8f6f4 v[76:79], v[24:31], v[218:225], v[76:79], v188, v188 op_sel_hi:[0,0,0]
	v_mfma_scale_f32_16x16x128_f8f6f4 v[68:71], v[16:23], v[218:225], v[68:71], v188, v188 op_sel_hi:[0,0,0]
	v_mfma_scale_f32_16x16x128_f8f6f4 v[60:63], v[24:31], v[226:233], v[60:63], v188, v188 op_sel_hi:[0,0,0]
	v_mfma_scale_f32_16x16x128_f8f6f4 v[56:59], v[16:23], v[226:233], v[56:59], v188, v188 op_sel_hi:[0,0,0]
	v_mfma_scale_f32_16x16x128_f8f6f4 v[44:47], v[24:31], v[234:241], v[44:47], v188, v188 op_sel_hi:[0,0,0]
	v_mfma_scale_f32_16x16x128_f8f6f4 v[40:43], v[16:23], v[234:241], v[40:43], v188, v188 op_sel_hi:[0,0,0]
	s_setprio 0
	s_setprio 3
	v_mfma_scale_f32_16x16x128_f8f6f4 v[84:87], v[8:15], v[210:217], v[84:87], v188, v188 op_sel_hi:[0,0,0]
	v_mfma_scale_f32_16x16x128_f8f6f4 v[80:83], v[0:7], v[210:217], v[80:83], v188, v188 op_sel_hi:[0,0,0]
	v_mfma_scale_f32_16x16x128_f8f6f4 v[72:75], v[8:15], v[218:225], v[72:75], v188, v188 op_sel_hi:[0,0,0]
	v_mfma_scale_f32_16x16x128_f8f6f4 v[64:67], v[0:7], v[218:225], v[64:67], v188, v188 op_sel_hi:[0,0,0]
	v_mfma_scale_f32_16x16x128_f8f6f4 v[52:55], v[8:15], v[226:233], v[52:55], v188, v188 op_sel_hi:[0,0,0]
	v_mfma_scale_f32_16x16x128_f8f6f4 v[48:51], v[0:7], v[226:233], v[48:51], v188, v188 op_sel_hi:[0,0,0]
	v_mfma_scale_f32_16x16x128_f8f6f4 v[36:39], v[8:15], v[234:241], v[36:39], v188, v188 op_sel_hi:[0,0,0]
	v_mfma_scale_f32_16x16x128_f8f6f4 v[32:35], v[0:7], v[234:241], v[32:35], v188, v188 op_sel_hi:[0,0,0]
	s_barrier
	s_setprio 0
	s_add_i32 s66, 0, 0x18000
	s_add_i32 s67, 0, 0x1c000
	ds_read_b128 v[0:3], v198
	ds_read_b128 v[4:7], v198 offset:1024
	ds_read_b128 v[8:11], v198 offset:2048
	ds_read_b128 v[12:15], v198 offset:3072
	ds_read_b128 v[16:19], v199
	ds_read_b128 v[20:23], v199 offset:1024
	ds_read_b128 v[24:27], v199 offset:2048
	ds_read_b128 v[28:31], v199 offset:3072
	s_add_u32 s0, s40, 0x80000
	s_addc_u32 s1, s41, 0
	s_mov_b32 m0, s47
	ds_read_b128 v[210:213], v195 offset:32768
	ds_read_b128 v[214:217], v195 offset:33792
	ds_read_b128 v[218:221], v195 offset:34816
	ds_read_b128 v[222:225], v195 offset:35840
	ds_read_b128 v[226:229], v195 offset:36864
	ds_read_b128 v[230:233], v195 offset:37888
	ds_read_b128 v[234:237], v195 offset:38912
	global_load_lds_dwordx4 v162, s[0:1]
	s_mov_b32 m0, s48
	ds_read_b128 v[238:241], v195 offset:39936
	global_load_lds_dwordx4 v166, s[0:1]
	s_waitcnt vmcnt(8)
	s_waitcnt lgkmcnt(0)
	s_setprio 3
	s_barrier
	v_mfma_scale_f32_16x16x128_f8f6f4 v[152:155], v[0:7], v[210:217], v[152:155], v188, v188 op_sel_hi:[0,0,0]
	v_mfma_scale_f32_16x16x128_f8f6f4 v[148:151], v[8:15], v[210:217], v[148:151], v188, v188 op_sel_hi:[0,0,0]
	v_mfma_scale_f32_16x16x128_f8f6f4 v[140:143], v[0:7], v[218:225], v[140:143], v188, v188 op_sel_hi:[0,0,0]
	v_mfma_scale_f32_16x16x128_f8f6f4 v[132:135], v[8:15], v[218:225], v[132:135], v188, v188 op_sel_hi:[0,0,0]
	v_mfma_scale_f32_16x16x128_f8f6f4 v[124:127], v[0:7], v[226:233], v[124:127], v188, v188 op_sel_hi:[0,0,0]
	v_mfma_scale_f32_16x16x128_f8f6f4 v[120:123], v[8:15], v[226:233], v[120:123], v188, v188 op_sel_hi:[0,0,0]
	v_mfma_scale_f32_16x16x128_f8f6f4 v[108:111], v[0:7], v[234:241], v[108:111], v188, v188 op_sel_hi:[0,0,0]
	v_mfma_scale_f32_16x16x128_f8f6f4 v[100:103], v[8:15], v[234:241], v[100:103], v188, v188 op_sel_hi:[0,0,0]
	s_setprio 0
	s_setprio 3
	v_mfma_scale_f32_16x16x128_f8f6f4 v[156:159], v[16:23], v[210:217], v[156:159], v188, v188 op_sel_hi:[0,0,0]
	v_mfma_scale_f32_16x16x128_f8f6f4 v[144:147], v[24:31], v[210:217], v[144:147], v188, v188 op_sel_hi:[0,0,0]
	v_mfma_scale_f32_16x16x128_f8f6f4 v[136:139], v[16:23], v[218:225], v[136:139], v188, v188 op_sel_hi:[0,0,0]
	v_mfma_scale_f32_16x16x128_f8f6f4 v[128:131], v[24:31], v[218:225], v[128:131], v188, v188 op_sel_hi:[0,0,0]
	v_mfma_scale_f32_16x16x128_f8f6f4 v[116:119], v[16:23], v[226:233], v[116:119], v188, v188 op_sel_hi:[0,0,0]
	v_mfma_scale_f32_16x16x128_f8f6f4 v[112:115], v[24:31], v[226:233], v[112:115], v188, v188 op_sel_hi:[0,0,0]
	v_mfma_scale_f32_16x16x128_f8f6f4 v[104:107], v[16:23], v[234:241], v[104:107], v188, v188 op_sel_hi:[0,0,0]
	v_mfma_scale_f32_16x16x128_f8f6f4 v[96:99], v[24:31], v[234:241], v[96:99], v188, v188 op_sel_hi:[0,0,0]
	s_barrier
	s_setprio 0
	s_add_i32 s0, s66, s45
	s_add_u32 s100, s38, 0x80
	s_addc_u32 s101, s39, 0
	s_mov_b32 m0, s0
	ds_read_b128 v[210:213], v195 offset:49152
	ds_read_b128 v[214:217], v195 offset:50176
	ds_read_b128 v[218:221], v195 offset:51200
	ds_read_b128 v[222:225], v195 offset:52224
	global_load_lds_dwordx4 v164, s[100:101]
	s_add_i32 m0, s0, 0x2000
	s_add_u32 s0, s38, 0x80080
	s_addc_u32 s1, s39, 0
	s_add_i32 s38, s67, s45
	global_load_lds_dwordx4 v168, s[100:101]
	s_mov_b32 m0, s38
	ds_read_b128 v[238:241], v195 offset:56320
	global_load_lds_dwordx4 v164, s[0:1]
	s_add_i32 m0, s38, 0x2000
	ds_read_b128 v[234:237], v195 offset:55296
	global_load_lds_dwordx4 v168, s[0:1]
	s_add_u32 s100, s40, 0x80
	s_addc_u32 s101, s41, 0
	s_mov_b32 m0, s51
	ds_read_b128 v[230:233], v195 offset:54272
	global_load_lds_dwordx4 v162, s[100:101]
	s_mov_b32 m0, s52
	ds_read_b128 v[226:229], v195 offset:53248
	global_load_lds_dwordx4 v166, s[100:101]
	s_waitcnt vmcnt(8)
	s_waitcnt lgkmcnt(0)
	s_setprio 3
	s_barrier
	v_mfma_scale_f32_16x16x128_f8f6f4 v[92:95], v[0:7], v[210:217], v[92:95], v188, v188 op_sel_hi:[0,0,0]
	v_mfma_scale_f32_16x16x128_f8f6f4 v[88:91], v[8:15], v[210:217], v[88:91], v188, v188 op_sel_hi:[0,0,0]
	v_mfma_scale_f32_16x16x128_f8f6f4 v[76:79], v[0:7], v[218:225], v[76:79], v188, v188 op_sel_hi:[0,0,0]
	v_mfma_scale_f32_16x16x128_f8f6f4 v[68:71], v[8:15], v[218:225], v[68:71], v188, v188 op_sel_hi:[0,0,0]
	v_mfma_scale_f32_16x16x128_f8f6f4 v[60:63], v[0:7], v[226:233], v[60:63], v188, v188 op_sel_hi:[0,0,0]
	v_mfma_scale_f32_16x16x128_f8f6f4 v[56:59], v[8:15], v[226:233], v[56:59], v188, v188 op_sel_hi:[0,0,0]
	v_mfma_scale_f32_16x16x128_f8f6f4 v[44:47], v[0:7], v[234:241], v[44:47], v188, v188 op_sel_hi:[0,0,0]
	v_mfma_scale_f32_16x16x128_f8f6f4 v[40:43], v[8:15], v[234:241], v[40:43], v188, v188 op_sel_hi:[0,0,0]
	s_setprio 0
	s_setprio 3
	v_mfma_scale_f32_16x16x128_f8f6f4 v[84:87], v[16:23], v[210:217], v[84:87], v188, v188 op_sel_hi:[0,0,0]
	v_mfma_scale_f32_16x16x128_f8f6f4 v[80:83], v[24:31], v[210:217], v[80:83], v188, v188 op_sel_hi:[0,0,0]
	v_mfma_scale_f32_16x16x128_f8f6f4 v[72:75], v[16:23], v[218:225], v[72:75], v188, v188 op_sel_hi:[0,0,0]
	v_mfma_scale_f32_16x16x128_f8f6f4 v[64:67], v[24:31], v[218:225], v[64:67], v188, v188 op_sel_hi:[0,0,0]
	v_mfma_scale_f32_16x16x128_f8f6f4 v[52:55], v[16:23], v[226:233], v[52:55], v188, v188 op_sel_hi:[0,0,0]
	v_mfma_scale_f32_16x16x128_f8f6f4 v[48:51], v[24:31], v[226:233], v[48:51], v188, v188 op_sel_hi:[0,0,0]
	v_mfma_scale_f32_16x16x128_f8f6f4 v[36:39], v[16:23], v[234:241], v[36:39], v188, v188 op_sel_hi:[0,0,0]
	v_mfma_scale_f32_16x16x128_f8f6f4 v[32:35], v[24:31], v[234:241], v[32:35], v188, v188 op_sel_hi:[0,0,0]
	s_barrier
	s_setprio 0
	s_add_u32 s36, s36, 0x100
	s_addc_u32 s37, s37, 0
	s_add_i32 s65, s65, 2
	s_add_u32 s63, s63, 0x100
	s_addc_u32 s64, s64, 0
	s_cmp_gt_u32 s65, 29
	s_cbranch_scc0 .LBB0_1833
	s_and_b64 vcc, exec, s[14:15]
	s_cbranch_vccz .LBB0_1836
	s_barrier

.LBB0_1974:
	v_add_u32_e32 v0, s65, v182
	v_add_u32_e32 v4, s66, v182
	ds_read_b128 v[24:27], v0
	ds_read_b128 v[28:31], v0 offset:1024
	ds_read_b128 v[16:19], v0 offset:2048
	ds_read_b128 v[20:23], v0 offset:3072
	ds_read_b128 v[8:11], v4
	ds_read_b128 v[12:15], v4 offset:1024
	ds_read_b128 v[0:3], v4 offset:2048
	ds_read_b128 v[4:7], v4 offset:3072
	s_add_i32 s35, s35, 2
	s_lshr_b32 s0, s35, 5
	s_mul_hi_u32 s1, s0, 0x4100000
	s_mul_i32 s0, s0, 0x4100000
	s_add_u32 s0, s46, s0
	s_addc_u32 s1, s47, s1
	s_and_b32 s37, s37, 0xf00
	s_add_u32 s0, s0, s37
	s_addc_u32 s1, s1, 0
	s_add_u32 s0, s0, 0x80080
	s_addc_u32 s1, s1, 0
	s_add_i32 m0, s43, 0xc000
	ds_read_b128 v[172:175], v184
	ds_read_b128 v[176:179], v184 offset:1024
	ds_read_b128 v[186:189], v184 offset:2048
	ds_read_b128 v[190:193], v184 offset:3072
	ds_read_b128 v[194:197], v184 offset:4096
	ds_read_b128 v[198:201], v184 offset:5120
	ds_read_b128 v[210:213], v184 offset:6144
	global_load_lds_dwordx4 v160, s[0:1]
	s_add_i32 m0, s43, 0xe000
	ds_read_b128 v[214:217], v184 offset:7168
	global_load_lds_dwordx4 v164, s[0:1]
	s_waitcnt vmcnt(8)
	s_waitcnt lgkmcnt(0)
	s_setprio 3
	s_barrier
	v_mfma_scale_f32_16x16x128_f8f6f4 v[156:159], v[24:31], v[172:179], v[156:159], v180, v180 op_sel_hi:[0,0,0]
	v_mfma_scale_f32_16x16x128_f8f6f4 v[152:155], v[16:23], v[172:179], v[152:155], v180, v180 op_sel_hi:[0,0,0]
	v_mfma_scale_f32_16x16x128_f8f6f4 v[144:147], v[24:31], v[186:193], v[144:147], v180, v180 op_sel_hi:[0,0,0]
	v_mfma_scale_f32_16x16x128_f8f6f4 v[136:139], v[16:23], v[186:193], v[136:139], v180, v180 op_sel_hi:[0,0,0]
	v_mfma_scale_f32_16x16x128_f8f6f4 v[128:131], v[24:31], v[194:201], v[128:131], v180, v180 op_sel_hi:[0,0,0]
	v_mfma_scale_f32_16x16x128_f8f6f4 v[120:123], v[16:23], v[194:201], v[120:123], v180, v180 op_sel_hi:[0,0,0]
	v_mfma_scale_f32_16x16x128_f8f6f4 v[112:115], v[24:31], v[210:217], v[112:115], v180, v180 op_sel_hi:[0,0,0]
	v_mfma_scale_f32_16x16x128_f8f6f4 v[104:107], v[16:23], v[210:217], v[104:107], v180, v180 op_sel_hi:[0,0,0]
	s_setprio 0
	s_setprio 3
	v_mfma_scale_f32_16x16x128_f8f6f4 v[148:151], v[8:15], v[172:179], v[148:151], v180, v180 op_sel_hi:[0,0,0]
	v_mfma_scale_f32_16x16x128_f8f6f4 v[140:143], v[0:7], v[172:179], v[140:143], v180, v180 op_sel_hi:[0,0,0]
	v_mfma_scale_f32_16x16x128_f8f6f4 v[132:135], v[8:15], v[186:193], v[132:135], v180, v180 op_sel_hi:[0,0,0]
	v_mfma_scale_f32_16x16x128_f8f6f4 v[124:127], v[0:7], v[186:193], v[124:127], v180, v180 op_sel_hi:[0,0,0]
	v_mfma_scale_f32_16x16x128_f8f6f4 v[116:119], v[8:15], v[194:201], v[116:119], v180, v180 op_sel_hi:[0,0,0]
	v_mfma_scale_f32_16x16x128_f8f6f4 v[108:111], v[0:7], v[194:201], v[108:111], v180, v180 op_sel_hi:[0,0,0]
	v_mfma_scale_f32_16x16x128_f8f6f4 v[100:103], v[8:15], v[210:217], v[100:103], v180, v180 op_sel_hi:[0,0,0]
	v_mfma_scale_f32_16x16x128_f8f6f4 v[96:99], v[0:7], v[210:217], v[96:99], v180, v180 op_sel_hi:[0,0,0]
	s_barrier
	s_setprio 0
	s_add_i32 s0, s65, s58
	s_mov_b32 m0, s0
	ds_read_b128 v[186:189], v184 offset:16384
	ds_read_b128 v[190:193], v184 offset:17408
	ds_read_b128 v[194:197], v184 offset:18432
	ds_read_b128 v[198:201], v184 offset:19456
	ds_read_b128 v[210:213], v184 offset:20480
	global_load_lds_dwordx4 v162, s[52:53]
	s_add_i32 m0, s0, 0x2000
	s_add_u32 s0, s52, 0x80000
	s_addc_u32 s1, s53, 0
	s_add_i32 s37, s66, s58
	global_load_lds_dwordx4 v166, s[52:53]
	s_mov_b32 m0, s37
	s_nop 0
	global_load_lds_dwordx4 v162, s[0:1]
	s_add_i32 m0, s37, 0x2000
	ds_read_b128 v[222:225], v184 offset:23552
	global_load_lds_dwordx4 v166, s[0:1]
	s_mov_b32 m0, s43
	ds_read_b128 v[218:221], v184 offset:22528
	global_load_lds_dwordx4 v160, s[54:55]
	s_mov_b32 m0, s59
	ds_read_b128 v[214:217], v184 offset:21504
	global_load_lds_dwordx4 v164, s[54:55]
	s_waitcnt vmcnt(8)
	s_waitcnt lgkmcnt(0)
	s_setprio 3
	s_barrier
	v_mfma_scale_f32_16x16x128_f8f6f4 v[92:95], v[24:31], v[186:193], v[92:95], v180, v180 op_sel_hi:[0,0,0]
	v_mfma_scale_f32_16x16x128_f8f6f4 v[88:91], v[16:23], v[186:193], v[88:91], v180, v180 op_sel_hi:[0,0,0]
	v_mfma_scale_f32_16x16x128_f8f6f4 v[80:83], v[24:31], v[194:201], v[80:83], v180, v180 op_sel_hi:[0,0,0]
	v_mfma_scale_f32_16x16x128_f8f6f4 v[72:75], v[16:23], v[194:201], v[72:75], v180, v180 op_sel_hi:[0,0,0]
	v_mfma_scale_f32_16x16x128_f8f6f4 v[64:67], v[24:31], v[210:217], v[64:67], v180, v180 op_sel_hi:[0,0,0]
	v_mfma_scale_f32_16x16x128_f8f6f4 v[56:59], v[16:23], v[210:217], v[56:59], v180, v180 op_sel_hi:[0,0,0]
	v_mfma_scale_f32_16x16x128_f8f6f4 v[48:51], v[24:31], v[218:225], v[48:51], v180, v180 op_sel_hi:[0,0,0]
	v_mfma_scale_f32_16x16x128_f8f6f4 v[40:43], v[16:23], v[218:225], v[40:43], v180, v180 op_sel_hi:[0,0,0]
	s_setprio 0
	s_setprio 3
	v_mfma_scale_f32_16x16x128_f8f6f4 v[84:87], v[8:15], v[186:193], v[84:87], v180, v180 op_sel_hi:[0,0,0]
	v_mfma_scale_f32_16x16x128_f8f6f4 v[76:79], v[0:7], v[186:193], v[76:79], v180, v180 op_sel_hi:[0,0,0]
	v_mfma_scale_f32_16x16x128_f8f6f4 v[68:71], v[8:15], v[194:201], v[68:71], v180, v180 op_sel_hi:[0,0,0]
	v_mfma_scale_f32_16x16x128_f8f6f4 v[60:63], v[0:7], v[194:201], v[60:63], v180, v180 op_sel_hi:[0,0,0]
	v_mfma_scale_f32_16x16x128_f8f6f4 v[52:55], v[8:15], v[210:217], v[52:55], v180, v180 op_sel_hi:[0,0,0]
	v_mfma_scale_f32_16x16x128_f8f6f4 v[44:47], v[0:7], v[210:217], v[44:47], v180, v180 op_sel_hi:[0,0,0]
	v_mfma_scale_f32_16x16x128_f8f6f4 v[36:39], v[8:15], v[218:225], v[36:39], v180, v180 op_sel_hi:[0,0,0]
	v_mfma_scale_f32_16x16x128_f8f6f4 v[32:35], v[0:7], v[218:225], v[32:35], v180, v180 op_sel_hi:[0,0,0]
	s_barrier
	s_setprio 0
	s_add_i32 s37, 0, 0x18000
	s_add_i32 s56, 0, 0x1c000
	v_add_u32_e32 v12, s37, v182
	v_add_u32_e32 v28, s56, v182
	ds_read_b128 v[0:3], v12
	ds_read_b128 v[4:7], v12 offset:1024
	ds_read_b128 v[8:11], v12 offset:2048
	ds_read_b128 v[12:15], v12 offset:3072
	ds_read_b128 v[16:19], v28
	ds_read_b128 v[20:23], v28 offset:1024
	ds_read_b128 v[24:27], v28 offset:2048
	ds_read_b128 v[28:31], v28 offset:3072
	s_add_u32 s0, s54, 0x80000
	s_addc_u32 s1, s55, 0
	s_mov_b32 m0, s60
	ds_read_b128 v[186:189], v184 offset:32768
	ds_read_b128 v[190:193], v184 offset:33792
	ds_read_b128 v[194:197], v184 offset:34816
	ds_read_b128 v[198:201], v184 offset:35840
	ds_read_b128 v[210:213], v184 offset:36864
	ds_read_b128 v[214:217], v184 offset:37888
	ds_read_b128 v[218:221], v184 offset:38912
	global_load_lds_dwordx4 v160, s[0:1]
	s_mov_b32 m0, s61
	ds_read_b128 v[222:225], v184 offset:39936
	global_load_lds_dwordx4 v164, s[0:1]
	s_waitcnt vmcnt(8)
	s_waitcnt lgkmcnt(0)
	s_setprio 3
	s_barrier
	v_mfma_scale_f32_16x16x128_f8f6f4 v[156:159], v[0:7], v[186:193], v[156:159], v180, v180 op_sel_hi:[0,0,0]
	v_mfma_scale_f32_16x16x128_f8f6f4 v[152:155], v[8:15], v[186:193], v[152:155], v180, v180 op_sel_hi:[0,0,0]
	v_mfma_scale_f32_16x16x128_f8f6f4 v[144:147], v[0:7], v[194:201], v[144:147], v180, v180 op_sel_hi:[0,0,0]
	v_mfma_scale_f32_16x16x128_f8f6f4 v[136:139], v[8:15], v[194:201], v[136:139], v180, v180 op_sel_hi:[0,0,0]
	v_mfma_scale_f32_16x16x128_f8f6f4 v[128:131], v[0:7], v[210:217], v[128:131], v180, v180 op_sel_hi:[0,0,0]
	v_mfma_scale_f32_16x16x128_f8f6f4 v[120:123], v[8:15], v[210:217], v[120:123], v180, v180 op_sel_hi:[0,0,0]
	v_mfma_scale_f32_16x16x128_f8f6f4 v[112:115], v[0:7], v[218:225], v[112:115], v180, v180 op_sel_hi:[0,0,0]
	v_mfma_scale_f32_16x16x128_f8f6f4 v[104:107], v[8:15], v[218:225], v[104:107], v180, v180 op_sel_hi:[0,0,0]
	s_setprio 0
	s_setprio 3
	v_mfma_scale_f32_16x16x128_f8f6f4 v[148:151], v[16:23], v[186:193], v[148:151], v180, v180 op_sel_hi:[0,0,0]
	v_mfma_scale_f32_16x16x128_f8f6f4 v[140:143], v[24:31], v[186:193], v[140:143], v180, v180 op_sel_hi:[0,0,0]
	v_mfma_scale_f32_16x16x128_f8f6f4 v[132:135], v[16:23], v[194:201], v[132:135], v180, v180 op_sel_hi:[0,0,0]
	v_mfma_scale_f32_16x16x128_f8f6f4 v[124:127], v[24:31], v[194:201], v[124:127], v180, v180 op_sel_hi:[0,0,0]
	v_mfma_scale_f32_16x16x128_f8f6f4 v[116:119], v[16:23], v[210:217], v[116:119], v180, v180 op_sel_hi:[0,0,0]
	v_mfma_scale_f32_16x16x128_f8f6f4 v[108:111], v[24:31], v[210:217], v[108:111], v180, v180 op_sel_hi:[0,0,0]
	v_mfma_scale_f32_16x16x128_f8f6f4 v[100:103], v[16:23], v[218:225], v[100:103], v180, v180 op_sel_hi:[0,0,0]
	v_mfma_scale_f32_16x16x128_f8f6f4 v[96:99], v[24:31], v[218:225], v[96:99], v180, v180 op_sel_hi:[0,0,0]
	s_barrier
	s_setprio 0
	s_add_i32 s0, s37, s58
	s_add_u32 s100, s52, 0x80
	s_addc_u32 s101, s53, 0
	s_mov_b32 m0, s0
	ds_read_b128 v[186:189], v184 offset:49152
	ds_read_b128 v[190:193], v184 offset:50176
	ds_read_b128 v[194:197], v184 offset:51200
	ds_read_b128 v[198:201], v184 offset:52224
	global_load_lds_dwordx4 v162, s[100:101]
	s_add_i32 m0, s0, 0x2000
	s_add_u32 s0, s52, 0x80080
	s_addc_u32 s1, s53, 0
	s_add_i32 s37, s56, s58
	global_load_lds_dwordx4 v166, s[100:101]
	s_mov_b32 m0, s37
	ds_read_b128 v[222:225], v184 offset:56320
	global_load_lds_dwordx4 v162, s[0:1]
	s_add_i32 m0, s37, 0x2000
	ds_read_b128 v[218:221], v184 offset:55296
	global_load_lds_dwordx4 v166, s[0:1]
	s_add_u32 s100, s54, 0x80
	s_addc_u32 s101, s55, 0
	s_mov_b32 m0, s62
	ds_read_b128 v[214:217], v184 offset:54272
	global_load_lds_dwordx4 v160, s[100:101]
	s_mov_b32 m0, s63
	ds_read_b128 v[210:213], v184 offset:53248
	global_load_lds_dwordx4 v164, s[100:101]
	s_waitcnt vmcnt(8)
	s_waitcnt lgkmcnt(0)
	s_setprio 3
	s_barrier
	v_mfma_scale_f32_16x16x128_f8f6f4 v[92:95], v[0:7], v[186:193], v[92:95], v180, v180 op_sel_hi:[0,0,0]
	v_mfma_scale_f32_16x16x128_f8f6f4 v[88:91], v[8:15], v[186:193], v[88:91], v180, v180 op_sel_hi:[0,0,0]
	v_mfma_scale_f32_16x16x128_f8f6f4 v[80:83], v[0:7], v[194:201], v[80:83], v180, v180 op_sel_hi:[0,0,0]
	v_mfma_scale_f32_16x16x128_f8f6f4 v[72:75], v[8:15], v[194:201], v[72:75], v180, v180 op_sel_hi:[0,0,0]
	v_mfma_scale_f32_16x16x128_f8f6f4 v[64:67], v[0:7], v[210:217], v[64:67], v180, v180 op_sel_hi:[0,0,0]
	v_mfma_scale_f32_16x16x128_f8f6f4 v[56:59], v[8:15], v[210:217], v[56:59], v180, v180 op_sel_hi:[0,0,0]
	v_mfma_scale_f32_16x16x128_f8f6f4 v[48:51], v[0:7], v[218:225], v[48:51], v180, v180 op_sel_hi:[0,0,0]
	v_mfma_scale_f32_16x16x128_f8f6f4 v[40:43], v[8:15], v[218:225], v[40:43], v180, v180 op_sel_hi:[0,0,0]
	s_setprio 0
	s_setprio 3
	v_mfma_scale_f32_16x16x128_f8f6f4 v[84:87], v[16:23], v[186:193], v[84:87], v180, v180 op_sel_hi:[0,0,0]
	v_mfma_scale_f32_16x16x128_f8f6f4 v[76:79], v[24:31], v[186:193], v[76:79], v180, v180 op_sel_hi:[0,0,0]
	v_mfma_scale_f32_16x16x128_f8f6f4 v[68:71], v[16:23], v[194:201], v[68:71], v180, v180 op_sel_hi:[0,0,0]
	v_mfma_scale_f32_16x16x128_f8f6f4 v[60:63], v[24:31], v[194:201], v[60:63], v180, v180 op_sel_hi:[0,0,0]
	v_mfma_scale_f32_16x16x128_f8f6f4 v[52:55], v[16:23], v[210:217], v[52:55], v180, v180 op_sel_hi:[0,0,0]
	v_mfma_scale_f32_16x16x128_f8f6f4 v[44:47], v[24:31], v[210:217], v[44:47], v180, v180 op_sel_hi:[0,0,0]
	v_mfma_scale_f32_16x16x128_f8f6f4 v[36:39], v[16:23], v[218:225], v[36:39], v180, v180 op_sel_hi:[0,0,0]
	v_mfma_scale_f32_16x16x128_f8f6f4 v[32:35], v[24:31], v[218:225], v[32:35], v180, v180 op_sel_hi:[0,0,0]
	s_barrier
	s_setprio 0
	s_cmpk_gt_u32 s35, 0x53
	s_mov_b32 s37, s6
	s_cbranch_scc1 .LBB0_1981
